# v_combo3 + top-k keys via ashr+bitop3 (one VALU less per key), third extraction loop peeled too, lane==round mask from SALU shift
# speedup vs baseline: 1.0105x; 1.0049x over previous
.LBB0_1346:
	s_mov_b32 s78, 0x10001
	s_mov_b32 s79, 0x10001
	v_add_co_u32_e32 v2, vcc, 0xe000, v0
	s_mov_b32 s40, 0
	s_nop 0
	v_addc_co_u32_e32 v3, vcc, 0, v1, vcc
	v_add_co_u32_e32 v4, vcc, 0xc000, v0
	s_mov_b64 s[0:1], vcc
	v_add_co_u32_e32 v6, vcc, 0xa000, v0
	s_nop 1
	v_addc_co_u32_e32 v7, vcc, 0, v1, vcc
	v_add_co_u32_e32 v8, vcc, 0x8000, v0
	s_nop 1
	v_addc_co_u32_e32 v9, vcc, 0, v1, vcc
	v_add_co_u32_e32 v10, vcc, 0x6000, v0
	s_nop 1
	v_addc_co_u32_e32 v11, vcc, 0, v1, vcc
	v_add_co_u32_e32 v14, vcc, 0x4000, v0
	s_nop 1
	v_addc_co_u32_e32 v15, vcc, 0, v1, vcc
	v_add_co_u32_e32 v18, vcc, 0x2000, v0
	s_nop 1
	v_addc_co_u32_e32 v19, vcc, 0, v1, vcc
	global_load_dwordx4 v[18:21], v[18:19], off
	s_nop 0
	global_load_dwordx4 v[22:25], v[0:1], off
	global_load_dwordx4 v[26:29], v[10:11], off
	global_load_dwordx4 v[30:33], v[14:15], off
	global_load_dwordx4 v[34:37], v[6:7], off
	global_load_dwordx4 v[38:41], v[8:9], off
	v_addc_co_u32_e64 v5, vcc, 0, v1, s[0:1]
	global_load_dwordx4 v[42:45], v[4:5], off
	global_load_dwordx4 v[46:49], v[2:3], off
	global_load_dwordx4 v[50:53], v[12:13], off
	global_load_dwordx4 v[54:57], v[12:13], off offset:64
	global_load_dwordx4 v[58:61], v[12:13], off offset:128
	global_load_dwordx4 v[62:65], v[12:13], off offset:192
	s_nop 0
	global_load_dwordx4 v[0:3], v[12:13], off offset:448
	global_load_dwordx4 v[4:7], v[12:13], off offset:384
	global_load_dwordx4 v[8:11], v[12:13], off offset:320
	s_nop 0
	global_load_dwordx4 v[12:15], v[12:13], off offset:256
	s_waitcnt lgkmcnt(0)
	s_barrier
	s_waitcnt vmcnt(14)
	ds_write_b128 v208, v[22:25]
	ds_write_b128 v209, v[18:21]
	s_waitcnt vmcnt(12)
	ds_write_b128 v210, v[30:33]
	ds_write_b128 v211, v[26:29]
	s_waitcnt vmcnt(10)
	ds_write_b128 v212, v[38:41]
	ds_write_b128 v213, v[34:37]
	s_waitcnt vmcnt(9)
	ds_write_b128 v214, v[42:45]
	s_waitcnt vmcnt(8)
	ds_write_b128 v215, v[46:49]
	s_waitcnt lgkmcnt(0)
	s_barrier
	ds_read_b128 v[18:21], v184
	ds_read_b128 v[22:25], v184 offset:64
	s_waitcnt vmcnt(7) lgkmcnt(1)
	v_mfma_f32_16x16x32_bf16 v[18:21], v[50:53], v[18:21], 0
	s_waitcnt vmcnt(6) lgkmcnt(0)
	v_mfma_f32_16x16x32_bf16 v[18:21], v[54:57], v[22:25], v[18:21]
	ds_read_b128 v[22:25], v184 offset:128
	ds_read_b128 v[26:29], v184 offset:192
	s_waitcnt vmcnt(5) lgkmcnt(1)
	v_mfma_f32_16x16x32_bf16 v[18:21], v[58:61], v[22:25], v[18:21]
	s_waitcnt vmcnt(4) lgkmcnt(0)
	v_mfma_f32_16x16x32_bf16 v[18:21], v[62:65], v[26:29], v[18:21]
	ds_read_b128 v[22:25], v184 offset:4352
	ds_read_b128 v[26:29], v184 offset:4416
	s_waitcnt lgkmcnt(1)
	v_mfma_f32_16x16x32_bf16 v[22:25], v[50:53], v[22:25], 0
	s_waitcnt lgkmcnt(0)
	v_mfma_f32_16x16x32_bf16 v[22:25], v[54:57], v[26:29], v[22:25]
	ds_read_b128 v[26:29], v184 offset:4480
	ds_read_b128 v[30:33], v184 offset:4544
	s_waitcnt lgkmcnt(1)
	v_mfma_f32_16x16x32_bf16 v[22:25], v[58:61], v[26:29], v[22:25]
	s_waitcnt lgkmcnt(0)
	v_mfma_f32_16x16x32_bf16 v[22:25], v[62:65], v[30:33], v[22:25]
	ds_read_b128 v[26:29], v184 offset:8704
	ds_read_b128 v[30:33], v184 offset:8768
	s_waitcnt lgkmcnt(1)
	v_mfma_f32_16x16x32_bf16 v[26:29], v[50:53], v[26:29], 0
	s_waitcnt lgkmcnt(0)
	v_mfma_f32_16x16x32_bf16 v[26:29], v[54:57], v[30:33], v[26:29]
	ds_read_b128 v[30:33], v184 offset:8832
	ds_read_b128 v[34:37], v184 offset:8896
	s_waitcnt lgkmcnt(1)
	v_mfma_f32_16x16x32_bf16 v[26:29], v[58:61], v[30:33], v[26:29]
	s_waitcnt lgkmcnt(0)
	v_mfma_f32_16x16x32_bf16 v[26:29], v[62:65], v[34:37], v[26:29]
	ds_read_b128 v[30:33], v184 offset:13056
	ds_read_b128 v[34:37], v184 offset:13120
	s_waitcnt lgkmcnt(1)
	v_mfma_f32_16x16x32_bf16 v[30:33], v[50:53], v[30:33], 0
	s_waitcnt lgkmcnt(0)
	v_mfma_f32_16x16x32_bf16 v[30:33], v[54:57], v[34:37], v[30:33]
	ds_read_b128 v[34:37], v184 offset:13184
	ds_read_b128 v[38:41], v184 offset:13248
	s_waitcnt lgkmcnt(1)
	v_mfma_f32_16x16x32_bf16 v[30:33], v[58:61], v[34:37], v[30:33]
	s_waitcnt lgkmcnt(0)
	v_mfma_f32_16x16x32_bf16 v[30:33], v[62:65], v[38:41], v[30:33]
	ds_read_b128 v[34:37], v184 offset:17408
	ds_read_b128 v[38:41], v184 offset:17472
	s_waitcnt lgkmcnt(1)
	v_mfma_f32_16x16x32_bf16 v[34:37], v[50:53], v[34:37], 0
	s_waitcnt lgkmcnt(0)
	v_mfma_f32_16x16x32_bf16 v[34:37], v[54:57], v[38:41], v[34:37]
	ds_read_b128 v[38:41], v184 offset:17536
	ds_read_b128 v[42:45], v184 offset:17600
	s_waitcnt lgkmcnt(1)
	v_mfma_f32_16x16x32_bf16 v[34:37], v[58:61], v[38:41], v[34:37]
	s_waitcnt lgkmcnt(0)
	v_mfma_f32_16x16x32_bf16 v[34:37], v[62:65], v[42:45], v[34:37]
	ds_read_b128 v[38:41], v184 offset:21760
	ds_read_b128 v[42:45], v184 offset:21824
	s_waitcnt lgkmcnt(1)
	v_mfma_f32_16x16x32_bf16 v[38:41], v[50:53], v[38:41], 0
	s_waitcnt lgkmcnt(0)
	v_mfma_f32_16x16x32_bf16 v[38:41], v[54:57], v[42:45], v[38:41]
	ds_read_b128 v[42:45], v184 offset:21888
	ds_read_b128 v[46:49], v184 offset:21952
	s_waitcnt lgkmcnt(1)
	v_mfma_f32_16x16x32_bf16 v[38:41], v[58:61], v[42:45], v[38:41]
	s_waitcnt lgkmcnt(0)
	v_mfma_f32_16x16x32_bf16 v[38:41], v[62:65], v[46:49], v[38:41]
	ds_read_b128 v[42:45], v184 offset:26112
	ds_read_b128 v[46:49], v184 offset:26176
	s_waitcnt lgkmcnt(1)
	v_mfma_f32_16x16x32_bf16 v[42:45], v[50:53], v[42:45], 0
	s_waitcnt lgkmcnt(0)
	v_mfma_f32_16x16x32_bf16 v[42:45], v[54:57], v[46:49], v[42:45]
	ds_read_b128 v[46:49], v184 offset:26240
	ds_read_b128 v[66:69], v184 offset:26304
	s_waitcnt lgkmcnt(1)
	v_mfma_f32_16x16x32_bf16 v[42:45], v[58:61], v[46:49], v[42:45]
	s_waitcnt lgkmcnt(0)
	v_mfma_f32_16x16x32_bf16 v[42:45], v[62:65], v[66:69], v[42:45]
	ds_read_b128 v[46:49], v184 offset:30464
	ds_read_b128 v[66:69], v184 offset:30528
	s_waitcnt lgkmcnt(1)
	v_mfma_f32_16x16x32_bf16 v[46:49], v[50:53], v[46:49], 0
	s_waitcnt lgkmcnt(0)
	v_mfma_f32_16x16x32_bf16 v[46:49], v[54:57], v[66:69], v[46:49]
	ds_read_b128 v[50:53], v184 offset:30592
	ds_read_b128 v[54:57], v184 offset:30656
	s_waitcnt lgkmcnt(1)
	v_mfma_f32_16x16x32_bf16 v[46:49], v[58:61], v[50:53], v[46:49]
	s_waitcnt lgkmcnt(0)
	v_mfma_f32_16x16x32_bf16 v[46:49], v[62:65], v[54:57], v[46:49]
	s_nop 7
	s_nop 1
	v_ashrrev_i32_e32 v50, 31, v49
	v_bitop3_b32 v49, v49, v50, v217 bitop3:0x1e
	v_and_or_b32 v49, v49, s67, v178
	v_ashrrev_i32_e32 v50, 31, v45
	v_bitop3_b32 v45, v45, v50, v217 bitop3:0x1e
	v_and_or_b32 v50, v45, s67, v177
	v_ashrrev_i32_e32 v45, 31, v41
	v_bitop3_b32 v41, v41, v45, v217 bitop3:0x1e
	v_and_or_b32 v51, v41, s67, v176
	v_ashrrev_i32_e32 v41, 31, v37
	v_bitop3_b32 v37, v37, v41, v217 bitop3:0x1e
	v_and_or_b32 v52, v37, s67, v175
	v_ashrrev_i32_e32 v37, 31, v33
	v_bitop3_b32 v33, v33, v37, v217 bitop3:0x1e
	v_and_or_b32 v53, v33, s67, v170
	v_ashrrev_i32_e32 v33, 31, v29
	v_bitop3_b32 v29, v29, v33, v217 bitop3:0x1e
	v_and_or_b32 v54, v29, s67, v181
	v_ashrrev_i32_e32 v29, 31, v25
	v_bitop3_b32 v25, v25, v29, v217 bitop3:0x1e
	v_and_or_b32 v55, v25, s67, v180
	v_ashrrev_i32_e32 v25, 31, v21
	v_bitop3_b32 v21, v21, v25, v217 bitop3:0x1e
	v_and_or_b32 v21, v21, s67, v179
	v_ashrrev_i32_e32 v25, 31, v48
	v_bitop3_b32 v25, v48, v25, v217 bitop3:0x1e
	v_and_or_b32 v41, v25, s67, v178
	v_ashrrev_i32_e32 v25, 31, v44
	v_bitop3_b32 v25, v44, v25, v217 bitop3:0x1e
	v_and_or_b32 v44, v25, s67, v177
	v_ashrrev_i32_e32 v25, 31, v40
	v_bitop3_b32 v25, v40, v25, v217 bitop3:0x1e
	v_and_or_b32 v40, v25, s67, v176
	v_ashrrev_i32_e32 v25, 31, v36
	v_bitop3_b32 v25, v36, v25, v217 bitop3:0x1e
	v_and_or_b32 v45, v25, s67, v175
	v_ashrrev_i32_e32 v25, 31, v32
	v_bitop3_b32 v25, v32, v25, v217 bitop3:0x1e
	v_and_or_b32 v48, v25, s67, v170
	v_ashrrev_i32_e32 v25, 31, v28
	v_bitop3_b32 v25, v28, v25, v217 bitop3:0x1e
	v_and_or_b32 v56, v25, s67, v181
	v_ashrrev_i32_e32 v25, 31, v24
	v_bitop3_b32 v24, v24, v25, v217 bitop3:0x1e
	v_and_or_b32 v57, v24, s67, v180
	v_ashrrev_i32_e32 v24, 31, v20
	v_bitop3_b32 v20, v20, v24, v217 bitop3:0x1e
	v_and_or_b32 v20, v20, s67, v179
	v_ashrrev_i32_e32 v24, 31, v47
	v_bitop3_b32 v24, v47, v24, v217 bitop3:0x1e
	v_and_or_b32 v32, v24, s67, v178
	v_min_u32_e32 v47, v52, v51
	v_ashrrev_i32_e32 v24, 31, v43
	v_bitop3_b32 v24, v43, v24, v217 bitop3:0x1e
	v_and_or_b32 v33, v24, s67, v177
	v_ashrrev_i32_e32 v24, 31, v39
	v_bitop3_b32 v24, v39, v24, v217 bitop3:0x1e
	v_and_or_b32 v36, v24, s67, v176
	v_ashrrev_i32_e32 v24, 31, v35
	v_bitop3_b32 v24, v35, v24, v217 bitop3:0x1e
	v_and_or_b32 v35, v24, s67, v175
	v_ashrrev_i32_e32 v24, 31, v31
	v_bitop3_b32 v24, v31, v24, v217 bitop3:0x1e
	v_and_or_b32 v31, v24, s67, v170
	v_ashrrev_i32_e32 v24, 31, v27
	v_bitop3_b32 v24, v27, v24, v217 bitop3:0x1e
	v_and_or_b32 v37, v24, s67, v181
	v_ashrrev_i32_e32 v24, 31, v23
	v_bitop3_b32 v23, v23, v24, v217 bitop3:0x1e
	v_and_or_b32 v39, v23, s67, v180
	v_ashrrev_i32_e32 v23, 31, v19
	v_bitop3_b32 v19, v19, v23, v217 bitop3:0x1e
	v_and_or_b32 v19, v19, s67, v179
	v_ashrrev_i32_e32 v23, 31, v46
	v_bitop3_b32 v23, v46, v23, v217 bitop3:0x1e
	v_and_or_b32 v23, v23, s67, v178
	v_ashrrev_i32_e32 v24, 31, v42
	v_bitop3_b32 v24, v42, v24, v217 bitop3:0x1e
	v_and_or_b32 v24, v24, s67, v177
	v_ashrrev_i32_e32 v25, 31, v38
	v_bitop3_b32 v25, v38, v25, v217 bitop3:0x1e
	v_and_or_b32 v25, v25, s67, v176
	v_ashrrev_i32_e32 v27, 31, v34
	v_bitop3_b32 v27, v34, v27, v217 bitop3:0x1e
	v_and_or_b32 v27, v27, s67, v175
	v_ashrrev_i32_e32 v28, 31, v30
	v_bitop3_b32 v28, v30, v28, v217 bitop3:0x1e
	v_and_or_b32 v28, v28, s67, v170
	v_ashrrev_i32_e32 v29, 31, v26
	v_bitop3_b32 v26, v26, v29, v217 bitop3:0x1e
	v_and_or_b32 v26, v26, s67, v181
	v_ashrrev_i32_e32 v29, 31, v22
	v_bitop3_b32 v22, v22, v29, v217 bitop3:0x1e
	v_and_or_b32 v22, v22, s67, v180
	v_ashrrev_i32_e32 v29, 31, v18
	v_bitop3_b32 v18, v18, v29, v217 bitop3:0x1e
	v_and_or_b32 v18, v18, s67, v179
	v_max_u32_e32 v29, v18, v22
	v_min_u32_e32 v18, v18, v22
	v_max_u32_e32 v22, v26, v28
	v_min_u32_e32 v26, v26, v28
	v_max_u32_e32 v28, v27, v25
	v_min_u32_e32 v25, v27, v25
	v_max_u32_e32 v27, v24, v23
	v_min_u32_e32 v23, v24, v23
	v_max_u32_e32 v24, v29, v22
	v_min_u32_e32 v22, v29, v22
	v_max_u32_e32 v29, v18, v26
	v_min_u32_e32 v18, v18, v26
	v_max_u32_e32 v26, v28, v27
	v_min_u32_e32 v27, v28, v27
	v_max_u32_e32 v28, v25, v23
	v_min_u32_e32 v23, v25, v23
	v_max_u32_e32 v25, v29, v22
	v_min_u32_e32 v29, v29, v22
	v_max_u32_e32 v30, v28, v27
	v_min_u32_e32 v27, v28, v27
	v_max_u32_e32 v22, v24, v26
	v_min_u32_e32 v24, v24, v26
	v_max_u32_e32 v26, v25, v30
	v_min_u32_e32 v25, v25, v30
	v_max_u32_e32 v28, v29, v27
	v_min_u32_e32 v29, v29, v27
	v_max_u32_e32 v27, v18, v23
	v_min_u32_e32 v23, v18, v23
	v_max_u32_e32 v18, v28, v24
	v_min_u32_e32 v28, v28, v24
	v_max_u32_e32 v30, v27, v25
	v_min_u32_e32 v34, v27, v25
	v_max_u32_e32 v24, v26, v18
	v_min_u32_e32 v25, v26, v18
	v_max_u32_e32 v26, v30, v28
	v_min_u32_e32 v27, v30, v28
	v_max_u32_e32 v28, v34, v29
	v_min_u32_e32 v29, v34, v29
	v_max_u32_e32 v18, v19, v39
	v_min_u32_e32 v19, v19, v39
	v_max_u32_e32 v30, v37, v31
	v_min_u32_e32 v31, v37, v31
	v_max_u32_e32 v34, v35, v36
	v_min_u32_e32 v35, v35, v36
	v_max_u32_e32 v36, v33, v32
	v_min_u32_e32 v32, v33, v32
	v_max_u32_e32 v33, v18, v30
	v_min_u32_e32 v18, v18, v30
	v_max_u32_e32 v30, v19, v31
	v_min_u32_e32 v19, v19, v31
	v_max_u32_e32 v31, v34, v36
	v_min_u32_e32 v34, v34, v36
	v_max_u32_e32 v36, v35, v32
	v_min_u32_e32 v32, v35, v32
	v_max_u32_e32 v35, v30, v18
	v_min_u32_e32 v18, v30, v18
	v_max_u32_e32 v37, v36, v34
	v_min_u32_e32 v34, v36, v34
	v_max_u32_e32 v30, v33, v31
	v_min_u32_e32 v33, v33, v31
	v_max_u32_e32 v36, v35, v37
	v_min_u32_e32 v35, v35, v37
	v_max_u32_e32 v37, v18, v34
	v_min_u32_e32 v18, v18, v34
	v_max_u32_e32 v34, v19, v32
	v_min_u32_e32 v31, v19, v32
	v_max_u32_e32 v19, v37, v33
	v_min_u32_e32 v37, v37, v33
	v_max_u32_e32 v38, v34, v35
	v_min_u32_e32 v39, v34, v35
	v_max_u32_e32 v32, v36, v19
	v_min_u32_e32 v33, v36, v19
	v_max_u32_e32 v34, v38, v37
	v_min_u32_e32 v35, v38, v37
	v_max_u32_e32 v36, v39, v18
	v_min_u32_e32 v37, v39, v18
	v_max_u32_e32 v18, v20, v57
	v_min_u32_e32 v19, v20, v57
	v_max_u32_e32 v20, v56, v48
	v_min_u32_e32 v38, v56, v48
	v_max_u32_e32 v39, v45, v40
	v_min_u32_e32 v40, v45, v40
	v_max_u32_e32 v42, v44, v41
	v_min_u32_e32 v41, v44, v41
	v_max_u32_e32 v43, v18, v20
	v_min_u32_e32 v18, v18, v20
	v_max_u32_e32 v20, v19, v38
	v_min_u32_e32 v19, v19, v38
	v_max_u32_e32 v44, v39, v42
	v_min_u32_e32 v38, v39, v42
	v_max_u32_e32 v39, v40, v41
	v_min_u32_e32 v40, v40, v41
	v_max_u32_e32 v41, v20, v18
	v_min_u32_e32 v18, v20, v18
	v_max_u32_e32 v20, v39, v38
	v_min_u32_e32 v39, v39, v38
	v_max_u32_e32 v38, v43, v44
	v_min_u32_e32 v42, v43, v44
	v_max_u32_e32 v43, v41, v20
	v_min_u32_e32 v20, v41, v20
	v_max_u32_e32 v41, v18, v39
	v_max_u32_e32 v44, v19, v40
	v_min_u32_e32 v18, v18, v39
	v_min_u32_e32 v39, v19, v40
	v_max_u32_e32 v19, v41, v42
	v_min_u32_e32 v45, v41, v42
	v_max_u32_e32 v46, v44, v20
	v_min_u32_e32 v20, v44, v20
	v_max_u32_e32 v40, v43, v19
	v_min_u32_e32 v41, v43, v19
	v_max_u32_e32 v42, v46, v45
	v_min_u32_e32 v43, v46, v45
	v_max_u32_e32 v44, v20, v18
	v_min_u32_e32 v45, v20, v18
	v_max_u32_e32 v18, v21, v55
	v_min_u32_e32 v19, v21, v55
	v_max_u32_e32 v20, v54, v53
	v_min_u32_e32 v21, v54, v53
	v_max_u32_e32 v46, v52, v51
	v_max_u32_e32 v48, v50, v49
	v_min_u32_e32 v49, v50, v49
	v_max_u32_e32 v50, v18, v20
	v_min_u32_e32 v18, v18, v20
	v_max_u32_e32 v20, v19, v21
	v_min_u32_e32 v19, v19, v21
	v_max_u32_e32 v21, v46, v48
	v_min_u32_e32 v46, v46, v48
	v_max_u32_e32 v48, v47, v49
	v_min_u32_e32 v47, v47, v49
	v_max_u32_e32 v49, v20, v18
	v_min_u32_e32 v18, v20, v18
	v_max_u32_e32 v20, v48, v46
	v_min_u32_e32 v48, v48, v46
	v_max_u32_e32 v46, v50, v21
	v_min_u32_e32 v21, v50, v21
	v_max_u32_e32 v50, v49, v20
	v_min_u32_e32 v20, v49, v20
	v_max_u32_e32 v49, v18, v48
	v_min_u32_e32 v18, v18, v48
	v_max_u32_e32 v48, v19, v47
	v_min_u32_e32 v47, v19, v47
	v_max_u32_e32 v19, v49, v21
	v_min_u32_e32 v21, v49, v21
	v_max_u32_e32 v51, v48, v20
	v_min_u32_e32 v20, v48, v20
	v_max_u32_e32 v48, v50, v19
	v_min_u32_e32 v49, v50, v19
	v_max_u32_e32 v50, v51, v21
	v_min_u32_e32 v51, v51, v21
	v_max_u32_e32 v52, v20, v18
	v_min_u32_e32 v53, v20, v18
	v_mov_b32_e32 v18, 0
	v_mov_b32_e32 v19, 0
	v_mov_b32_e32 v20, 0
	v_mov_b32_e32 v21, 0
.LBB0_1347:
	v_max_u32_dpp v55, v30, v30 row_ror:1 row_mask:0xf bank_mask:0xf bound_ctrl:1
	v_max_u32_dpp v54, v22, v22 row_ror:1 row_mask:0xf bank_mask:0xf bound_ctrl:1
	v_max_u32_dpp v56, v38, v38 row_ror:1 row_mask:0xf bank_mask:0xf bound_ctrl:1
	v_max_u32_dpp v55, v55, v55 row_ror:2 row_mask:0xf bank_mask:0xf bound_ctrl:1
	v_max_u32_dpp v57, v46, v46 row_ror:1 row_mask:0xf bank_mask:0xf bound_ctrl:1
	v_max_u32_dpp v54, v54, v54 row_ror:2 row_mask:0xf bank_mask:0xf bound_ctrl:1
	v_max_u32_dpp v56, v56, v56 row_ror:2 row_mask:0xf bank_mask:0xf bound_ctrl:1
	v_max_u32_dpp v55, v55, v55 row_ror:4 row_mask:0xf bank_mask:0xf bound_ctrl:1
	v_max_u32_dpp v57, v57, v57 row_ror:2 row_mask:0xf bank_mask:0xf bound_ctrl:1
	v_max_u32_dpp v54, v54, v54 row_ror:4 row_mask:0xf bank_mask:0xf bound_ctrl:1
	v_max_u32_dpp v56, v56, v56 row_ror:4 row_mask:0xf bank_mask:0xf bound_ctrl:1
	v_max_u32_dpp v55, v55, v55 row_ror:8 row_mask:0xf bank_mask:0xf bound_ctrl:1
	v_max_u32_dpp v57, v57, v57 row_ror:4 row_mask:0xf bank_mask:0xf bound_ctrl:1
	v_max_u32_dpp v54, v54, v54 row_ror:8 row_mask:0xf bank_mask:0xf bound_ctrl:1
	v_max_u32_dpp v56, v56, v56 row_ror:8 row_mask:0xf bank_mask:0xf bound_ctrl:1
	v_cmp_eq_u32_e64 s[0:1], v30, v55
	v_max_u32_dpp v57, v57, v57 row_ror:8 row_mask:0xf bank_mask:0xf bound_ctrl:1
	v_cmp_eq_u32_e32 vcc, v22, v54
	v_cndmask_b32_e64 v30, v30, v32, s[0:1]
	v_cndmask_b32_e64 v32, v32, v33, s[0:1]
	v_cndmask_b32_e64 v33, v33, v34, s[0:1]
	v_cndmask_b32_e64 v34, v34, v35, s[0:1]
	v_cndmask_b32_e64 v35, v35, v36, s[0:1]
	v_cndmask_b32_e64 v36, v36, v37, s[0:1]
	v_cndmask_b32_e64 v37, v37, v31, s[0:1]
	v_cndmask_b32_e64 v31, v31, 0, s[0:1]
	v_cmp_eq_u32_e64 s[0:1], v38, v56
	v_cndmask_b32_e32 v22, v22, v24, vcc
	v_cndmask_b32_e32 v24, v24, v25, vcc
	v_cndmask_b32_e32 v25, v25, v26, vcc
	v_cndmask_b32_e32 v26, v26, v27, vcc
	v_cndmask_b32_e32 v27, v27, v28, vcc
	v_cndmask_b32_e32 v28, v28, v29, vcc
	v_cndmask_b32_e32 v29, v29, v23, vcc
	v_cndmask_b32_e64 v23, v23, 0, vcc
	s_lshl_b64 vcc, s[78:79], s40
	v_cndmask_b32_e64 v38, v38, v40, s[0:1]
	v_cndmask_b32_e64 v40, v40, v41, s[0:1]
	v_cndmask_b32_e64 v41, v41, v42, s[0:1]
	v_cndmask_b32_e64 v42, v42, v43, s[0:1]
	v_cndmask_b32_e64 v43, v43, v44, s[0:1]
	v_cndmask_b32_e64 v44, v44, v45, s[0:1]
	v_cndmask_b32_e64 v45, v45, v39, s[0:1]
	v_cndmask_b32_e64 v39, v39, 0, s[0:1]
	v_cmp_eq_u32_e64 s[0:1], v46, v57
	s_add_i32 s40, s40, 1
	v_cndmask_b32_e32 v18, v18, v54, vcc
	v_cndmask_b32_e32 v19, v19, v55, vcc
	v_cndmask_b32_e32 v20, v20, v56, vcc
	v_cndmask_b32_e64 v46, v46, v48, s[0:1]
	v_cndmask_b32_e64 v48, v48, v49, s[0:1]
	v_cndmask_b32_e64 v49, v49, v50, s[0:1]
	v_cndmask_b32_e64 v50, v50, v51, s[0:1]
	v_cndmask_b32_e64 v51, v51, v52, s[0:1]
	v_cndmask_b32_e64 v52, v52, v53, s[0:1]
	v_cndmask_b32_e64 v53, v53, v47, s[0:1]
	v_cndmask_b32_e64 v47, v47, 0, s[0:1]
	s_cmp_lg_u32 s40, 8
	v_cndmask_b32_e32 v21, v21, v57, vcc
	s_cbranch_scc1 .LBB0_1347
	v_max_u32_dpp v55, v30, v30 row_ror:1 row_mask:0xf bank_mask:0xf bound_ctrl:1
	v_max_u32_dpp v54, v22, v22 row_ror:1 row_mask:0xf bank_mask:0xf bound_ctrl:1
	v_max_u32_dpp v56, v38, v38 row_ror:1 row_mask:0xf bank_mask:0xf bound_ctrl:1
	v_max_u32_dpp v55, v55, v55 row_ror:2 row_mask:0xf bank_mask:0xf bound_ctrl:1
	v_max_u32_dpp v57, v46, v46 row_ror:1 row_mask:0xf bank_mask:0xf bound_ctrl:1
	v_max_u32_dpp v54, v54, v54 row_ror:2 row_mask:0xf bank_mask:0xf bound_ctrl:1
	v_max_u32_dpp v56, v56, v56 row_ror:2 row_mask:0xf bank_mask:0xf bound_ctrl:1
	v_max_u32_dpp v55, v55, v55 row_ror:4 row_mask:0xf bank_mask:0xf bound_ctrl:1
	v_max_u32_dpp v57, v57, v57 row_ror:2 row_mask:0xf bank_mask:0xf bound_ctrl:1
	v_max_u32_dpp v54, v54, v54 row_ror:4 row_mask:0xf bank_mask:0xf bound_ctrl:1
	v_max_u32_dpp v56, v56, v56 row_ror:4 row_mask:0xf bank_mask:0xf bound_ctrl:1
	v_max_u32_dpp v55, v55, v55 row_ror:8 row_mask:0xf bank_mask:0xf bound_ctrl:1
	v_max_u32_dpp v57, v57, v57 row_ror:4 row_mask:0xf bank_mask:0xf bound_ctrl:1
	v_max_u32_dpp v54, v54, v54 row_ror:8 row_mask:0xf bank_mask:0xf bound_ctrl:1
	v_max_u32_dpp v56, v56, v56 row_ror:8 row_mask:0xf bank_mask:0xf bound_ctrl:1
	v_cmp_eq_u32_e64 s[0:1], v30, v55
	v_max_u32_dpp v57, v57, v57 row_ror:8 row_mask:0xf bank_mask:0xf bound_ctrl:1
	v_cmp_eq_u32_e32 vcc, v22, v54
	v_cndmask_b32_e64 v30, v30, v32, s[0:1]
	v_cndmask_b32_e64 v32, v32, v33, s[0:1]
	v_cndmask_b32_e64 v33, v33, v34, s[0:1]
	v_cndmask_b32_e64 v34, v34, v35, s[0:1]
	v_cndmask_b32_e64 v35, v35, v36, s[0:1]
	v_cndmask_b32_e64 v36, v36, v37, s[0:1]
	v_cndmask_b32_e64 v37, v37, v31, s[0:1]
	v_cmp_eq_u32_e64 s[0:1], v38, v56
	v_cndmask_b32_e32 v22, v22, v24, vcc
	v_cndmask_b32_e32 v24, v24, v25, vcc
	v_cndmask_b32_e32 v25, v25, v26, vcc
	v_cndmask_b32_e32 v26, v26, v27, vcc
	v_cndmask_b32_e32 v27, v27, v28, vcc
	v_cndmask_b32_e32 v28, v28, v29, vcc
	v_cndmask_b32_e32 v29, v29, v23, vcc
	s_lshl_b64 vcc, s[78:79], s40
	v_cndmask_b32_e64 v38, v38, v40, s[0:1]
	v_cndmask_b32_e64 v40, v40, v41, s[0:1]
	v_cndmask_b32_e64 v41, v41, v42, s[0:1]
	v_cndmask_b32_e64 v42, v42, v43, s[0:1]
	v_cndmask_b32_e64 v43, v43, v44, s[0:1]
	v_cndmask_b32_e64 v44, v44, v45, s[0:1]
	v_cndmask_b32_e64 v45, v45, v39, s[0:1]
	v_cmp_eq_u32_e64 s[0:1], v46, v57
	s_add_i32 s40, s40, 1
	v_cndmask_b32_e32 v18, v18, v54, vcc
	v_cndmask_b32_e32 v19, v19, v55, vcc
	v_cndmask_b32_e32 v20, v20, v56, vcc
	v_cndmask_b32_e64 v46, v46, v48, s[0:1]
	v_cndmask_b32_e64 v48, v48, v49, s[0:1]
	v_cndmask_b32_e64 v49, v49, v50, s[0:1]
	v_cndmask_b32_e64 v50, v50, v51, s[0:1]
	v_cndmask_b32_e64 v51, v51, v52, s[0:1]
	v_cndmask_b32_e64 v52, v52, v53, s[0:1]
	v_cndmask_b32_e64 v53, v53, v47, s[0:1]
	v_cndmask_b32_e32 v21, v21, v57, vcc
	v_max_u32_dpp v55, v30, v30 row_ror:1 row_mask:0xf bank_mask:0xf bound_ctrl:1
	v_max_u32_dpp v54, v22, v22 row_ror:1 row_mask:0xf bank_mask:0xf bound_ctrl:1
	v_max_u32_dpp v56, v38, v38 row_ror:1 row_mask:0xf bank_mask:0xf bound_ctrl:1
	v_max_u32_dpp v55, v55, v55 row_ror:2 row_mask:0xf bank_mask:0xf bound_ctrl:1
	v_max_u32_dpp v57, v46, v46 row_ror:1 row_mask:0xf bank_mask:0xf bound_ctrl:1
	v_max_u32_dpp v54, v54, v54 row_ror:2 row_mask:0xf bank_mask:0xf bound_ctrl:1
	v_max_u32_dpp v56, v56, v56 row_ror:2 row_mask:0xf bank_mask:0xf bound_ctrl:1
	v_max_u32_dpp v55, v55, v55 row_ror:4 row_mask:0xf bank_mask:0xf bound_ctrl:1
	v_max_u32_dpp v57, v57, v57 row_ror:2 row_mask:0xf bank_mask:0xf bound_ctrl:1
	v_max_u32_dpp v54, v54, v54 row_ror:4 row_mask:0xf bank_mask:0xf bound_ctrl:1
	v_max_u32_dpp v56, v56, v56 row_ror:4 row_mask:0xf bank_mask:0xf bound_ctrl:1
	v_max_u32_dpp v55, v55, v55 row_ror:8 row_mask:0xf bank_mask:0xf bound_ctrl:1
	v_max_u32_dpp v57, v57, v57 row_ror:4 row_mask:0xf bank_mask:0xf bound_ctrl:1
	v_max_u32_dpp v54, v54, v54 row_ror:8 row_mask:0xf bank_mask:0xf bound_ctrl:1
	v_max_u32_dpp v56, v56, v56 row_ror:8 row_mask:0xf bank_mask:0xf bound_ctrl:1
	v_cmp_eq_u32_e64 s[0:1], v30, v55
	v_max_u32_dpp v57, v57, v57 row_ror:8 row_mask:0xf bank_mask:0xf bound_ctrl:1
	v_cmp_eq_u32_e32 vcc, v22, v54
	v_cndmask_b32_e64 v30, v30, v32, s[0:1]
	v_cndmask_b32_e64 v32, v32, v33, s[0:1]
	v_cndmask_b32_e64 v33, v33, v34, s[0:1]
	v_cndmask_b32_e64 v34, v34, v35, s[0:1]
	v_cndmask_b32_e64 v35, v35, v36, s[0:1]
	v_cndmask_b32_e64 v36, v36, v37, s[0:1]
	v_cmp_eq_u32_e64 s[0:1], v38, v56
	v_cndmask_b32_e32 v22, v22, v24, vcc
	v_cndmask_b32_e32 v24, v24, v25, vcc
	v_cndmask_b32_e32 v25, v25, v26, vcc
	v_cndmask_b32_e32 v26, v26, v27, vcc
	v_cndmask_b32_e32 v27, v27, v28, vcc
	v_cndmask_b32_e32 v28, v28, v29, vcc
	s_lshl_b64 vcc, s[78:79], s40
	v_cndmask_b32_e64 v38, v38, v40, s[0:1]
	v_cndmask_b32_e64 v40, v40, v41, s[0:1]
	v_cndmask_b32_e64 v41, v41, v42, s[0:1]
	v_cndmask_b32_e64 v42, v42, v43, s[0:1]
	v_cndmask_b32_e64 v43, v43, v44, s[0:1]
	v_cndmask_b32_e64 v44, v44, v45, s[0:1]
	v_cmp_eq_u32_e64 s[0:1], v46, v57
	s_add_i32 s40, s40, 1
	v_cndmask_b32_e32 v18, v18, v54, vcc
	v_cndmask_b32_e32 v19, v19, v55, vcc
	v_cndmask_b32_e32 v20, v20, v56, vcc
	v_cndmask_b32_e64 v46, v46, v48, s[0:1]
	v_cndmask_b32_e64 v48, v48, v49, s[0:1]
	v_cndmask_b32_e64 v49, v49, v50, s[0:1]
	v_cndmask_b32_e64 v50, v50, v51, s[0:1]
	v_cndmask_b32_e64 v51, v51, v52, s[0:1]
	v_cndmask_b32_e64 v52, v52, v53, s[0:1]
	v_cndmask_b32_e32 v21, v21, v57, vcc
	v_max_u32_dpp v55, v30, v30 row_ror:1 row_mask:0xf bank_mask:0xf bound_ctrl:1
	v_max_u32_dpp v54, v22, v22 row_ror:1 row_mask:0xf bank_mask:0xf bound_ctrl:1
	v_max_u32_dpp v56, v38, v38 row_ror:1 row_mask:0xf bank_mask:0xf bound_ctrl:1
	v_max_u32_dpp v55, v55, v55 row_ror:2 row_mask:0xf bank_mask:0xf bound_ctrl:1
	v_max_u32_dpp v57, v46, v46 row_ror:1 row_mask:0xf bank_mask:0xf bound_ctrl:1
	v_max_u32_dpp v54, v54, v54 row_ror:2 row_mask:0xf bank_mask:0xf bound_ctrl:1
	v_max_u32_dpp v56, v56, v56 row_ror:2 row_mask:0xf bank_mask:0xf bound_ctrl:1
	v_max_u32_dpp v55, v55, v55 row_ror:4 row_mask:0xf bank_mask:0xf bound_ctrl:1
	v_max_u32_dpp v57, v57, v57 row_ror:2 row_mask:0xf bank_mask:0xf bound_ctrl:1
	v_max_u32_dpp v54, v54, v54 row_ror:4 row_mask:0xf bank_mask:0xf bound_ctrl:1
	v_max_u32_dpp v56, v56, v56 row_ror:4 row_mask:0xf bank_mask:0xf bound_ctrl:1
	v_max_u32_dpp v55, v55, v55 row_ror:8 row_mask:0xf bank_mask:0xf bound_ctrl:1
	v_max_u32_dpp v57, v57, v57 row_ror:4 row_mask:0xf bank_mask:0xf bound_ctrl:1
	v_max_u32_dpp v54, v54, v54 row_ror:8 row_mask:0xf bank_mask:0xf bound_ctrl:1
	v_max_u32_dpp v56, v56, v56 row_ror:8 row_mask:0xf bank_mask:0xf bound_ctrl:1
	v_cmp_eq_u32_e64 s[0:1], v30, v55
	v_max_u32_dpp v57, v57, v57 row_ror:8 row_mask:0xf bank_mask:0xf bound_ctrl:1
	v_cmp_eq_u32_e32 vcc, v22, v54
	v_cndmask_b32_e64 v30, v30, v32, s[0:1]
	v_cndmask_b32_e64 v32, v32, v33, s[0:1]
	v_cndmask_b32_e64 v33, v33, v34, s[0:1]
	v_cndmask_b32_e64 v34, v34, v35, s[0:1]
	v_cndmask_b32_e64 v35, v35, v36, s[0:1]
	v_cmp_eq_u32_e64 s[0:1], v38, v56
	v_cndmask_b32_e32 v22, v22, v24, vcc
	v_cndmask_b32_e32 v24, v24, v25, vcc
	v_cndmask_b32_e32 v25, v25, v26, vcc
	v_cndmask_b32_e32 v26, v26, v27, vcc
	v_cndmask_b32_e32 v27, v27, v28, vcc
	s_lshl_b64 vcc, s[78:79], s40
	v_cndmask_b32_e64 v38, v38, v40, s[0:1]
	v_cndmask_b32_e64 v40, v40, v41, s[0:1]
	v_cndmask_b32_e64 v41, v41, v42, s[0:1]
	v_cndmask_b32_e64 v42, v42, v43, s[0:1]
	v_cndmask_b32_e64 v43, v43, v44, s[0:1]
	v_cmp_eq_u32_e64 s[0:1], v46, v57
	s_add_i32 s40, s40, 1
	v_cndmask_b32_e32 v18, v18, v54, vcc
	v_cndmask_b32_e32 v19, v19, v55, vcc
	v_cndmask_b32_e32 v20, v20, v56, vcc
	v_cndmask_b32_e64 v46, v46, v48, s[0:1]
	v_cndmask_b32_e64 v48, v48, v49, s[0:1]
	v_cndmask_b32_e64 v49, v49, v50, s[0:1]
	v_cndmask_b32_e64 v50, v50, v51, s[0:1]
	v_cndmask_b32_e64 v51, v51, v52, s[0:1]
	v_cndmask_b32_e32 v21, v21, v57, vcc
	v_max_u32_dpp v55, v30, v30 row_ror:1 row_mask:0xf bank_mask:0xf bound_ctrl:1
	v_max_u32_dpp v54, v22, v22 row_ror:1 row_mask:0xf bank_mask:0xf bound_ctrl:1
	v_max_u32_dpp v56, v38, v38 row_ror:1 row_mask:0xf bank_mask:0xf bound_ctrl:1
	v_max_u32_dpp v55, v55, v55 row_ror:2 row_mask:0xf bank_mask:0xf bound_ctrl:1
	v_max_u32_dpp v57, v46, v46 row_ror:1 row_mask:0xf bank_mask:0xf bound_ctrl:1
	v_max_u32_dpp v54, v54, v54 row_ror:2 row_mask:0xf bank_mask:0xf bound_ctrl:1
	v_max_u32_dpp v56, v56, v56 row_ror:2 row_mask:0xf bank_mask:0xf bound_ctrl:1
	v_max_u32_dpp v55, v55, v55 row_ror:4 row_mask:0xf bank_mask:0xf bound_ctrl:1
	v_max_u32_dpp v57, v57, v57 row_ror:2 row_mask:0xf bank_mask:0xf bound_ctrl:1
	v_max_u32_dpp v54, v54, v54 row_ror:4 row_mask:0xf bank_mask:0xf bound_ctrl:1
	v_max_u32_dpp v56, v56, v56 row_ror:4 row_mask:0xf bank_mask:0xf bound_ctrl:1
	v_max_u32_dpp v55, v55, v55 row_ror:8 row_mask:0xf bank_mask:0xf bound_ctrl:1
	v_max_u32_dpp v57, v57, v57 row_ror:4 row_mask:0xf bank_mask:0xf bound_ctrl:1
	v_max_u32_dpp v54, v54, v54 row_ror:8 row_mask:0xf bank_mask:0xf bound_ctrl:1
	v_max_u32_dpp v56, v56, v56 row_ror:8 row_mask:0xf bank_mask:0xf bound_ctrl:1
	v_cmp_eq_u32_e64 s[0:1], v30, v55
	v_max_u32_dpp v57, v57, v57 row_ror:8 row_mask:0xf bank_mask:0xf bound_ctrl:1
	v_cmp_eq_u32_e32 vcc, v22, v54
	v_cndmask_b32_e64 v30, v30, v32, s[0:1]
	v_cndmask_b32_e64 v32, v32, v33, s[0:1]
	v_cndmask_b32_e64 v33, v33, v34, s[0:1]
	v_cndmask_b32_e64 v34, v34, v35, s[0:1]
	v_cmp_eq_u32_e64 s[0:1], v38, v56
	v_cndmask_b32_e32 v22, v22, v24, vcc
	v_cndmask_b32_e32 v24, v24, v25, vcc
	v_cndmask_b32_e32 v25, v25, v26, vcc
	v_cndmask_b32_e32 v26, v26, v27, vcc
	s_lshl_b64 vcc, s[78:79], s40
	v_cndmask_b32_e64 v38, v38, v40, s[0:1]
	v_cndmask_b32_e64 v40, v40, v41, s[0:1]
	v_cndmask_b32_e64 v41, v41, v42, s[0:1]
	v_cndmask_b32_e64 v42, v42, v43, s[0:1]
	v_cmp_eq_u32_e64 s[0:1], v46, v57
	s_add_i32 s40, s40, 1
	v_cndmask_b32_e32 v18, v18, v54, vcc
	v_cndmask_b32_e32 v19, v19, v55, vcc
	v_cndmask_b32_e32 v20, v20, v56, vcc
	v_cndmask_b32_e64 v46, v46, v48, s[0:1]
	v_cndmask_b32_e64 v48, v48, v49, s[0:1]
	v_cndmask_b32_e64 v49, v49, v50, s[0:1]
	v_cndmask_b32_e64 v50, v50, v51, s[0:1]
	v_cndmask_b32_e32 v21, v21, v57, vcc
	v_max_u32_dpp v55, v30, v30 row_ror:1 row_mask:0xf bank_mask:0xf bound_ctrl:1
	v_max_u32_dpp v54, v22, v22 row_ror:1 row_mask:0xf bank_mask:0xf bound_ctrl:1
	v_max_u32_dpp v56, v38, v38 row_ror:1 row_mask:0xf bank_mask:0xf bound_ctrl:1
	v_max_u32_dpp v55, v55, v55 row_ror:2 row_mask:0xf bank_mask:0xf bound_ctrl:1
	v_max_u32_dpp v57, v46, v46 row_ror:1 row_mask:0xf bank_mask:0xf bound_ctrl:1
	v_max_u32_dpp v54, v54, v54 row_ror:2 row_mask:0xf bank_mask:0xf bound_ctrl:1
	v_max_u32_dpp v56, v56, v56 row_ror:2 row_mask:0xf bank_mask:0xf bound_ctrl:1
	v_max_u32_dpp v55, v55, v55 row_ror:4 row_mask:0xf bank_mask:0xf bound_ctrl:1
	v_max_u32_dpp v57, v57, v57 row_ror:2 row_mask:0xf bank_mask:0xf bound_ctrl:1
	v_max_u32_dpp v54, v54, v54 row_ror:4 row_mask:0xf bank_mask:0xf bound_ctrl:1
	v_max_u32_dpp v56, v56, v56 row_ror:4 row_mask:0xf bank_mask:0xf bound_ctrl:1
	v_max_u32_dpp v55, v55, v55 row_ror:8 row_mask:0xf bank_mask:0xf bound_ctrl:1
	v_max_u32_dpp v57, v57, v57 row_ror:4 row_mask:0xf bank_mask:0xf bound_ctrl:1
	v_max_u32_dpp v54, v54, v54 row_ror:8 row_mask:0xf bank_mask:0xf bound_ctrl:1
	v_max_u32_dpp v56, v56, v56 row_ror:8 row_mask:0xf bank_mask:0xf bound_ctrl:1
	v_cmp_eq_u32_e64 s[0:1], v30, v55
	v_max_u32_dpp v57, v57, v57 row_ror:8 row_mask:0xf bank_mask:0xf bound_ctrl:1
	v_cmp_eq_u32_e32 vcc, v22, v54
	v_cndmask_b32_e64 v30, v30, v32, s[0:1]
	v_cndmask_b32_e64 v32, v32, v33, s[0:1]
	v_cndmask_b32_e64 v33, v33, v34, s[0:1]
	v_cmp_eq_u32_e64 s[0:1], v38, v56
	v_cndmask_b32_e32 v22, v22, v24, vcc
	v_cndmask_b32_e32 v24, v24, v25, vcc
	v_cndmask_b32_e32 v25, v25, v26, vcc
	s_lshl_b64 vcc, s[78:79], s40
	v_cndmask_b32_e64 v38, v38, v40, s[0:1]
	v_cndmask_b32_e64 v40, v40, v41, s[0:1]
	v_cndmask_b32_e64 v41, v41, v42, s[0:1]
	v_cmp_eq_u32_e64 s[0:1], v46, v57
	s_add_i32 s40, s40, 1
	v_cndmask_b32_e32 v18, v18, v54, vcc
	v_cndmask_b32_e32 v19, v19, v55, vcc
	v_cndmask_b32_e32 v20, v20, v56, vcc
	v_cndmask_b32_e64 v46, v46, v48, s[0:1]
	v_cndmask_b32_e64 v48, v48, v49, s[0:1]
	v_cndmask_b32_e64 v49, v49, v50, s[0:1]
	v_cndmask_b32_e32 v21, v21, v57, vcc
	v_max_u32_dpp v55, v30, v30 row_ror:1 row_mask:0xf bank_mask:0xf bound_ctrl:1
	v_max_u32_dpp v54, v22, v22 row_ror:1 row_mask:0xf bank_mask:0xf bound_ctrl:1
	v_max_u32_dpp v56, v38, v38 row_ror:1 row_mask:0xf bank_mask:0xf bound_ctrl:1
	v_max_u32_dpp v55, v55, v55 row_ror:2 row_mask:0xf bank_mask:0xf bound_ctrl:1
	v_max_u32_dpp v57, v46, v46 row_ror:1 row_mask:0xf bank_mask:0xf bound_ctrl:1
	v_max_u32_dpp v54, v54, v54 row_ror:2 row_mask:0xf bank_mask:0xf bound_ctrl:1
	v_max_u32_dpp v56, v56, v56 row_ror:2 row_mask:0xf bank_mask:0xf bound_ctrl:1
	v_max_u32_dpp v55, v55, v55 row_ror:4 row_mask:0xf bank_mask:0xf bound_ctrl:1
	v_max_u32_dpp v57, v57, v57 row_ror:2 row_mask:0xf bank_mask:0xf bound_ctrl:1
	v_max_u32_dpp v54, v54, v54 row_ror:4 row_mask:0xf bank_mask:0xf bound_ctrl:1
	v_max_u32_dpp v56, v56, v56 row_ror:4 row_mask:0xf bank_mask:0xf bound_ctrl:1
	v_max_u32_dpp v55, v55, v55 row_ror:8 row_mask:0xf bank_mask:0xf bound_ctrl:1
	v_max_u32_dpp v57, v57, v57 row_ror:4 row_mask:0xf bank_mask:0xf bound_ctrl:1
	v_max_u32_dpp v54, v54, v54 row_ror:8 row_mask:0xf bank_mask:0xf bound_ctrl:1
	v_max_u32_dpp v56, v56, v56 row_ror:8 row_mask:0xf bank_mask:0xf bound_ctrl:1
	v_cmp_eq_u32_e64 s[0:1], v30, v55
	v_max_u32_dpp v57, v57, v57 row_ror:8 row_mask:0xf bank_mask:0xf bound_ctrl:1
	v_cmp_eq_u32_e32 vcc, v22, v54
	v_cndmask_b32_e64 v30, v30, v32, s[0:1]
	v_cndmask_b32_e64 v32, v32, v33, s[0:1]
	v_cmp_eq_u32_e64 s[0:1], v38, v56
	v_cndmask_b32_e32 v22, v22, v24, vcc
	v_cndmask_b32_e32 v24, v24, v25, vcc
	s_lshl_b64 vcc, s[78:79], s40
	v_cndmask_b32_e64 v38, v38, v40, s[0:1]
	v_cndmask_b32_e64 v40, v40, v41, s[0:1]
	v_cmp_eq_u32_e64 s[0:1], v46, v57
	s_add_i32 s40, s40, 1
	v_cndmask_b32_e32 v18, v18, v54, vcc
	v_cndmask_b32_e32 v19, v19, v55, vcc
	v_cndmask_b32_e32 v20, v20, v56, vcc
	v_cndmask_b32_e64 v46, v46, v48, s[0:1]
	v_cndmask_b32_e64 v48, v48, v49, s[0:1]
	v_cndmask_b32_e32 v21, v21, v57, vcc
	v_max_u32_dpp v55, v30, v30 row_ror:1 row_mask:0xf bank_mask:0xf bound_ctrl:1
	v_max_u32_dpp v54, v22, v22 row_ror:1 row_mask:0xf bank_mask:0xf bound_ctrl:1
	v_max_u32_dpp v56, v38, v38 row_ror:1 row_mask:0xf bank_mask:0xf bound_ctrl:1
	v_max_u32_dpp v55, v55, v55 row_ror:2 row_mask:0xf bank_mask:0xf bound_ctrl:1
	v_max_u32_dpp v57, v46, v46 row_ror:1 row_mask:0xf bank_mask:0xf bound_ctrl:1
	v_max_u32_dpp v54, v54, v54 row_ror:2 row_mask:0xf bank_mask:0xf bound_ctrl:1
	v_max_u32_dpp v56, v56, v56 row_ror:2 row_mask:0xf bank_mask:0xf bound_ctrl:1
	v_max_u32_dpp v55, v55, v55 row_ror:4 row_mask:0xf bank_mask:0xf bound_ctrl:1
	v_max_u32_dpp v57, v57, v57 row_ror:2 row_mask:0xf bank_mask:0xf bound_ctrl:1
	v_max_u32_dpp v54, v54, v54 row_ror:4 row_mask:0xf bank_mask:0xf bound_ctrl:1
	v_max_u32_dpp v56, v56, v56 row_ror:4 row_mask:0xf bank_mask:0xf bound_ctrl:1
	v_max_u32_dpp v55, v55, v55 row_ror:8 row_mask:0xf bank_mask:0xf bound_ctrl:1
	v_max_u32_dpp v57, v57, v57 row_ror:4 row_mask:0xf bank_mask:0xf bound_ctrl:1
	v_max_u32_dpp v54, v54, v54 row_ror:8 row_mask:0xf bank_mask:0xf bound_ctrl:1
	v_max_u32_dpp v56, v56, v56 row_ror:8 row_mask:0xf bank_mask:0xf bound_ctrl:1
	v_cmp_eq_u32_e64 s[0:1], v30, v55
	v_max_u32_dpp v57, v57, v57 row_ror:8 row_mask:0xf bank_mask:0xf bound_ctrl:1
	v_cmp_eq_u32_e32 vcc, v22, v54
	v_cndmask_b32_e64 v30, v30, v32, s[0:1]
	v_cmp_eq_u32_e64 s[0:1], v38, v56
	v_cndmask_b32_e32 v22, v22, v24, vcc
	s_lshl_b64 vcc, s[78:79], s40
	v_cndmask_b32_e64 v38, v38, v40, s[0:1]
	v_cmp_eq_u32_e64 s[0:1], v46, v57
	s_add_i32 s40, s40, 1
	v_cndmask_b32_e32 v18, v18, v54, vcc
	v_cndmask_b32_e32 v19, v19, v55, vcc
	v_cndmask_b32_e32 v20, v20, v56, vcc
	v_cndmask_b32_e64 v46, v46, v48, s[0:1]
	v_cndmask_b32_e32 v21, v21, v57, vcc
	v_max_u32_dpp v55, v30, v30 row_ror:1 row_mask:0xf bank_mask:0xf bound_ctrl:1
	v_max_u32_dpp v54, v22, v22 row_ror:1 row_mask:0xf bank_mask:0xf bound_ctrl:1
	v_max_u32_dpp v56, v38, v38 row_ror:1 row_mask:0xf bank_mask:0xf bound_ctrl:1
	v_max_u32_dpp v55, v55, v55 row_ror:2 row_mask:0xf bank_mask:0xf bound_ctrl:1
	v_max_u32_dpp v57, v46, v46 row_ror:1 row_mask:0xf bank_mask:0xf bound_ctrl:1
	v_max_u32_dpp v54, v54, v54 row_ror:2 row_mask:0xf bank_mask:0xf bound_ctrl:1
	v_max_u32_dpp v56, v56, v56 row_ror:2 row_mask:0xf bank_mask:0xf bound_ctrl:1
	v_max_u32_dpp v55, v55, v55 row_ror:4 row_mask:0xf bank_mask:0xf bound_ctrl:1
	v_max_u32_dpp v57, v57, v57 row_ror:2 row_mask:0xf bank_mask:0xf bound_ctrl:1
	v_max_u32_dpp v54, v54, v54 row_ror:4 row_mask:0xf bank_mask:0xf bound_ctrl:1
	v_max_u32_dpp v56, v56, v56 row_ror:4 row_mask:0xf bank_mask:0xf bound_ctrl:1
	v_max_u32_dpp v55, v55, v55 row_ror:8 row_mask:0xf bank_mask:0xf bound_ctrl:1
	v_max_u32_dpp v57, v57, v57 row_ror:4 row_mask:0xf bank_mask:0xf bound_ctrl:1
	v_max_u32_dpp v54, v54, v54 row_ror:8 row_mask:0xf bank_mask:0xf bound_ctrl:1
	v_max_u32_dpp v56, v56, v56 row_ror:8 row_mask:0xf bank_mask:0xf bound_ctrl:1
	v_max_u32_dpp v57, v57, v57 row_ror:8 row_mask:0xf bank_mask:0xf bound_ctrl:1
	s_lshl_b64 vcc, s[78:79], s40
	v_cndmask_b32_e32 v18, v18, v54, vcc
	v_cndmask_b32_e32 v19, v19, v55, vcc
	v_cndmask_b32_e32 v20, v20, v56, vcc
	v_cndmask_b32_e32 v21, v21, v57, vcc
	ds_read_b128 v[22:25], v184 offset:34816
	ds_read_b128 v[26:29], v184 offset:34880
	s_waitcnt vmcnt(0) lgkmcnt(1)
	v_mfma_f32_16x16x32_bf16 v[22:25], v[12:15], v[22:25], 0
	s_waitcnt lgkmcnt(0)
	v_mfma_f32_16x16x32_bf16 v[22:25], v[8:11], v[26:29], v[22:25]
	ds_read_b128 v[26:29], v184 offset:34944
	s_waitcnt lgkmcnt(0)
	v_mfma_f32_16x16x32_bf16 v[22:25], v[4:7], v[26:29], v[22:25]
	ds_read_b128 v[26:29], v184 offset:35008
	s_waitcnt lgkmcnt(0)
	v_mfma_f32_16x16x32_bf16 v[22:25], v[0:3], v[26:29], v[22:25]
	ds_read_b128 v[26:29], v184 offset:39168
	ds_read_b128 v[30:33], v184 offset:39232
	s_waitcnt lgkmcnt(1)
	v_mfma_f32_16x16x32_bf16 v[26:29], v[12:15], v[26:29], 0
	s_waitcnt lgkmcnt(0)
	v_mfma_f32_16x16x32_bf16 v[26:29], v[8:11], v[30:33], v[26:29]
	ds_read_b128 v[30:33], v184 offset:39296
	ds_read_b128 v[34:37], v184 offset:39360
	s_waitcnt lgkmcnt(1)
	v_mfma_f32_16x16x32_bf16 v[26:29], v[4:7], v[30:33], v[26:29]
	s_waitcnt lgkmcnt(0)
	v_mfma_f32_16x16x32_bf16 v[26:29], v[0:3], v[34:37], v[26:29]
	ds_read_b128 v[30:33], v184 offset:43520
	ds_read_b128 v[34:37], v184 offset:43584
	s_waitcnt lgkmcnt(1)
	v_mfma_f32_16x16x32_bf16 v[30:33], v[12:15], v[30:33], 0
	s_waitcnt lgkmcnt(0)
	v_mfma_f32_16x16x32_bf16 v[30:33], v[8:11], v[34:37], v[30:33]
	ds_read_b128 v[34:37], v184 offset:43648
	ds_read_b128 v[38:41], v184 offset:43712
	s_waitcnt lgkmcnt(1)
	v_mfma_f32_16x16x32_bf16 v[30:33], v[4:7], v[34:37], v[30:33]
	s_waitcnt lgkmcnt(0)
	v_mfma_f32_16x16x32_bf16 v[30:33], v[0:3], v[38:41], v[30:33]
	ds_read_b128 v[34:37], v184 offset:47872
	ds_read_b128 v[38:41], v184 offset:47936
	s_waitcnt lgkmcnt(1)
	v_mfma_f32_16x16x32_bf16 v[34:37], v[12:15], v[34:37], 0
	s_waitcnt lgkmcnt(0)
	v_mfma_f32_16x16x32_bf16 v[34:37], v[8:11], v[38:41], v[34:37]
	ds_read_b128 v[38:41], v184 offset:48000
	ds_read_b128 v[42:45], v184 offset:48064
	s_waitcnt lgkmcnt(1)
	v_mfma_f32_16x16x32_bf16 v[34:37], v[4:7], v[38:41], v[34:37]
	s_waitcnt lgkmcnt(0)
	v_mfma_f32_16x16x32_bf16 v[34:37], v[0:3], v[42:45], v[34:37]
	ds_read_b128 v[38:41], v184 offset:52224
	ds_read_b128 v[42:45], v184 offset:52288
	s_waitcnt lgkmcnt(1)
	v_mfma_f32_16x16x32_bf16 v[38:41], v[12:15], v[38:41], 0
	s_waitcnt lgkmcnt(0)
	v_mfma_f32_16x16x32_bf16 v[38:41], v[8:11], v[42:45], v[38:41]
	ds_read_b128 v[42:45], v184 offset:52352
	ds_read_b128 v[46:49], v184 offset:52416
	s_waitcnt lgkmcnt(1)
	v_mfma_f32_16x16x32_bf16 v[38:41], v[4:7], v[42:45], v[38:41]
	s_waitcnt lgkmcnt(0)
	v_mfma_f32_16x16x32_bf16 v[38:41], v[0:3], v[46:49], v[38:41]
	ds_read_b128 v[42:45], v184 offset:56576
	ds_read_b128 v[46:49], v184 offset:56640
	s_waitcnt lgkmcnt(1)
	v_mfma_f32_16x16x32_bf16 v[42:45], v[12:15], v[42:45], 0
	s_waitcnt lgkmcnt(0)
	v_mfma_f32_16x16x32_bf16 v[42:45], v[8:11], v[46:49], v[42:45]
	ds_read_b128 v[46:49], v184 offset:56704
	ds_read_b128 v[50:53], v184 offset:56768
	s_waitcnt lgkmcnt(1)
	v_mfma_f32_16x16x32_bf16 v[42:45], v[4:7], v[46:49], v[42:45]
	s_waitcnt lgkmcnt(0)
	v_mfma_f32_16x16x32_bf16 v[42:45], v[0:3], v[50:53], v[42:45]
	ds_read_b128 v[46:49], v184 offset:60928
	ds_read_b128 v[50:53], v184 offset:60992
	s_waitcnt lgkmcnt(1)
	v_mfma_f32_16x16x32_bf16 v[46:49], v[12:15], v[46:49], 0
	s_waitcnt lgkmcnt(0)
	v_mfma_f32_16x16x32_bf16 v[46:49], v[8:11], v[50:53], v[46:49]
	ds_read_b128 v[50:53], v184 offset:61056
	ds_read_b128 v[54:57], v184 offset:61120
	s_waitcnt lgkmcnt(1)
	v_mfma_f32_16x16x32_bf16 v[46:49], v[4:7], v[50:53], v[46:49]
	s_waitcnt lgkmcnt(0)
	v_mfma_f32_16x16x32_bf16 v[46:49], v[0:3], v[54:57], v[46:49]
	ds_read_b128 v[50:53], v184 offset:65280
	ds_read_b128 v[54:57], v184 offset:65344
	s_waitcnt lgkmcnt(1)
	v_mfma_f32_16x16x32_bf16 v[12:15], v[12:15], v[50:53], 0
	s_waitcnt lgkmcnt(0)
	v_mfma_f32_16x16x32_bf16 v[8:11], v[8:11], v[54:57], v[12:15]
	s_nop 5
	ds_read_b128 v[12:15], v184 offset:65408
	ds_read_b128 v[50:53], v184 offset:65472
	s_waitcnt lgkmcnt(1)
	v_mfma_f32_16x16x32_bf16 v[4:7], v[4:7], v[12:15], v[8:11]
	s_waitcnt lgkmcnt(0)
	v_mfma_f32_16x16x32_bf16 v[0:3], v[0:3], v[50:53], v[4:7]
	s_nop 7
	s_mov_b32 s40, 0
	v_ashrrev_i32_e32 v4, 31, v3
	v_bitop3_b32 v3, v3, v4, v217 bitop3:0x1e
	v_and_or_b32 v3, v3, s67, v178
	v_ashrrev_i32_e32 v4, 31, v49
	v_bitop3_b32 v4, v49, v4, v217 bitop3:0x1e
	v_and_or_b32 v49, v4, s67, v177
	v_ashrrev_i32_e32 v4, 31, v45
	v_bitop3_b32 v4, v45, v4, v217 bitop3:0x1e
	v_and_or_b32 v45, v4, s67, v176
	v_ashrrev_i32_e32 v4, 31, v41
	v_bitop3_b32 v4, v41, v4, v217 bitop3:0x1e
	v_and_or_b32 v41, v4, s67, v175
	v_ashrrev_i32_e32 v4, 31, v37
	v_bitop3_b32 v4, v37, v4, v217 bitop3:0x1e
	v_and_or_b32 v37, v4, s67, v170
	v_ashrrev_i32_e32 v4, 31, v33
	v_bitop3_b32 v4, v33, v4, v217 bitop3:0x1e
	v_and_or_b32 v50, v4, s67, v181
	v_ashrrev_i32_e32 v4, 31, v29
	v_bitop3_b32 v4, v29, v4, v217 bitop3:0x1e
	v_and_or_b32 v51, v4, s67, v180
	v_ashrrev_i32_e32 v4, 31, v25
	v_bitop3_b32 v4, v25, v4, v217 bitop3:0x1e
	v_and_or_b32 v52, v4, s67, v179
	v_ashrrev_i32_e32 v4, 31, v2
	v_bitop3_b32 v2, v2, v4, v217 bitop3:0x1e
	v_and_or_b32 v2, v2, s67, v178
	v_ashrrev_i32_e32 v4, 31, v48
	v_bitop3_b32 v4, v48, v4, v217 bitop3:0x1e
	v_and_or_b32 v29, v4, s67, v177
	v_ashrrev_i32_e32 v4, 31, v44
	v_bitop3_b32 v4, v44, v4, v217 bitop3:0x1e
	v_and_or_b32 v33, v4, s67, v176
	v_ashrrev_i32_e32 v4, 31, v40
	v_bitop3_b32 v4, v40, v4, v217 bitop3:0x1e
	v_and_or_b32 v40, v4, s67, v175
	v_ashrrev_i32_e32 v4, 31, v36
	v_bitop3_b32 v4, v36, v4, v217 bitop3:0x1e
	v_and_or_b32 v36, v4, s67, v170
	v_ashrrev_i32_e32 v4, 31, v32
	v_bitop3_b32 v4, v32, v4, v217 bitop3:0x1e
	v_and_or_b32 v32, v4, s67, v181
	v_ashrrev_i32_e32 v4, 31, v28
	v_bitop3_b32 v4, v28, v4, v217 bitop3:0x1e
	v_and_or_b32 v28, v4, s67, v180
	v_ashrrev_i32_e32 v4, 31, v24
	v_bitop3_b32 v4, v24, v4, v217 bitop3:0x1e
	v_and_or_b32 v44, v4, s67, v179
	v_ashrrev_i32_e32 v4, 31, v1
	v_bitop3_b32 v1, v1, v4, v217 bitop3:0x1e
	v_and_or_b32 v1, v1, s67, v178
	v_ashrrev_i32_e32 v4, 31, v47
	v_bitop3_b32 v4, v47, v4, v217 bitop3:0x1e
	v_and_or_b32 v12, v4, s67, v177
	v_ashrrev_i32_e32 v4, 31, v43
	v_bitop3_b32 v4, v43, v4, v217 bitop3:0x1e
	v_and_or_b32 v13, v4, s67, v176
	v_ashrrev_i32_e32 v4, 31, v39
	v_bitop3_b32 v4, v39, v4, v217 bitop3:0x1e
	v_and_or_b32 v14, v4, s67, v175
	v_ashrrev_i32_e32 v4, 31, v35
	v_bitop3_b32 v4, v35, v4, v217 bitop3:0x1e
	v_and_or_b32 v15, v4, s67, v170
	v_max_u32_e32 v35, v41, v45
	v_ashrrev_i32_e32 v4, 31, v31
	v_bitop3_b32 v4, v31, v4, v217 bitop3:0x1e
	v_and_or_b32 v24, v4, s67, v181
	v_max_u32_e32 v31, v29, v2
	v_ashrrev_i32_e32 v4, 31, v27
	v_bitop3_b32 v4, v27, v4, v217 bitop3:0x1e
	v_and_or_b32 v25, v4, s67, v180
	v_min_u32_e32 v2, v29, v2
	v_ashrrev_i32_e32 v4, 31, v23
	v_bitop3_b32 v4, v23, v4, v217 bitop3:0x1e
	v_and_or_b32 v23, v4, s67, v179
	v_ashrrev_i32_e32 v4, 31, v0
	v_bitop3_b32 v0, v0, v4, v217 bitop3:0x1e
	v_and_or_b32 v0, v0, s67, v178
	v_ashrrev_i32_e32 v4, 31, v46
	v_bitop3_b32 v4, v46, v4, v217 bitop3:0x1e
	v_and_or_b32 v4, v4, s67, v177
	v_ashrrev_i32_e32 v5, 31, v42
	v_bitop3_b32 v5, v42, v5, v217 bitop3:0x1e
	v_and_or_b32 v5, v5, s67, v176
	v_ashrrev_i32_e32 v6, 31, v38
	v_bitop3_b32 v6, v38, v6, v217 bitop3:0x1e
	v_and_or_b32 v6, v6, s67, v175
	v_ashrrev_i32_e32 v7, 31, v34
	v_bitop3_b32 v7, v34, v7, v217 bitop3:0x1e
	v_and_or_b32 v7, v7, s67, v170
	v_ashrrev_i32_e32 v8, 31, v30
	v_bitop3_b32 v8, v30, v8, v217 bitop3:0x1e
	v_and_or_b32 v8, v8, s67, v181
	v_ashrrev_i32_e32 v9, 31, v26
	v_bitop3_b32 v9, v26, v9, v217 bitop3:0x1e
	v_and_or_b32 v9, v9, s67, v180
	v_ashrrev_i32_e32 v10, 31, v22
	v_bitop3_b32 v10, v22, v10, v217 bitop3:0x1e
	v_and_or_b32 v10, v10, s67, v179
	v_max_u32_e32 v11, v10, v9
	v_min_u32_e32 v9, v10, v9
	v_max_u32_e32 v10, v8, v7
	v_min_u32_e32 v7, v8, v7
	v_max_u32_e32 v8, v6, v5
	v_min_u32_e32 v5, v6, v5
	v_max_u32_e32 v6, v4, v0
	v_min_u32_e32 v0, v4, v0
	v_max_u32_e32 v22, v11, v10
	v_min_u32_e32 v4, v11, v10
	v_max_u32_e32 v10, v9, v7
	v_min_u32_e32 v7, v9, v7
	v_max_u32_e32 v9, v8, v6
	v_min_u32_e32 v6, v8, v6
	v_max_u32_e32 v8, v5, v0
	v_min_u32_e32 v0, v5, v0
	v_max_u32_e32 v5, v10, v4
	v_min_u32_e32 v10, v10, v4
	v_max_u32_e32 v11, v8, v6
	v_min_u32_e32 v6, v8, v6
	v_max_u32_e32 v4, v22, v9
	v_min_u32_e32 v8, v22, v9
	v_max_u32_e32 v9, v5, v11
	v_min_u32_e32 v11, v5, v11
	v_max_u32_e32 v22, v10, v6
	v_min_u32_e32 v26, v10, v6
	v_max_u32_e32 v6, v7, v0
	v_min_u32_e32 v5, v7, v0
	v_max_u32_e32 v0, v22, v8
	v_min_u32_e32 v10, v22, v8
	v_max_u32_e32 v22, v6, v11
	v_min_u32_e32 v11, v6, v11
	v_max_u32_e32 v6, v9, v0
	v_min_u32_e32 v7, v9, v0
	v_max_u32_e32 v8, v22, v10
	v_min_u32_e32 v9, v22, v10
	v_max_u32_e32 v0, v23, v25
	v_min_u32_e32 v22, v23, v25
	v_max_u32_e32 v23, v24, v15
	v_min_u32_e32 v15, v24, v15
	v_max_u32_e32 v24, v14, v13
	v_min_u32_e32 v13, v14, v13
	v_max_u32_e32 v14, v12, v1
	v_min_u32_e32 v1, v12, v1
	v_max_u32_e32 v25, v0, v23
	v_min_u32_e32 v0, v0, v23
	v_max_u32_e32 v12, v22, v15
	v_min_u32_e32 v15, v22, v15
	v_max_u32_e32 v22, v24, v14
	v_min_u32_e32 v14, v24, v14
	v_max_u32_e32 v23, v13, v1
	v_min_u32_e32 v1, v13, v1
	v_max_u32_e32 v13, v12, v0
	v_min_u32_e32 v0, v12, v0
	v_max_u32_e32 v24, v23, v14
	v_min_u32_e32 v14, v23, v14
	v_max_u32_e32 v12, v25, v22
	v_min_u32_e32 v22, v25, v22
	v_max_u32_e32 v23, v13, v24
	v_min_u32_e32 v24, v13, v24
	v_max_u32_e32 v25, v0, v14
	v_min_u32_e32 v0, v0, v14
	v_max_u32_e32 v14, v15, v1
	v_max_u32_e32 v10, v11, v26
	v_min_u32_e32 v11, v11, v26
	v_min_u32_e32 v13, v15, v1
	v_max_u32_e32 v1, v25, v22
	v_min_u32_e32 v25, v25, v22
	v_max_u32_e32 v26, v14, v24
	v_min_u32_e32 v27, v14, v24
	v_max_u32_e32 v14, v23, v1
	v_min_u32_e32 v15, v23, v1
	v_max_u32_e32 v22, v26, v25
	v_min_u32_e32 v23, v26, v25
	v_max_u32_e32 v24, v27, v0
	v_min_u32_e32 v25, v27, v0
	v_max_u32_e32 v0, v44, v28
	v_min_u32_e32 v1, v44, v28
	v_max_u32_e32 v26, v32, v36
	v_min_u32_e32 v27, v32, v36
	v_max_u32_e32 v28, v40, v33
	v_min_u32_e32 v30, v40, v33
	v_max_u32_e32 v29, v0, v26
	v_min_u32_e32 v0, v0, v26
	v_max_u32_e32 v26, v1, v27
	v_min_u32_e32 v1, v1, v27
	v_max_u32_e32 v27, v28, v31
	v_min_u32_e32 v28, v28, v31
	v_max_u32_e32 v31, v30, v2
	v_min_u32_e32 v2, v30, v2
	v_max_u32_e32 v30, v26, v0
	v_min_u32_e32 v0, v26, v0
	v_max_u32_e32 v32, v31, v28
	v_min_u32_e32 v28, v31, v28
	v_max_u32_e32 v26, v29, v27
	v_min_u32_e32 v29, v29, v27
	v_max_u32_e32 v31, v30, v32
	v_min_u32_e32 v30, v30, v32
	v_max_u32_e32 v32, v0, v28
	v_min_u32_e32 v0, v0, v28
	v_max_u32_e32 v28, v1, v2
	v_min_u32_e32 v27, v1, v2
	v_max_u32_e32 v1, v32, v29
	v_min_u32_e32 v2, v32, v29
	v_max_u32_e32 v32, v28, v30
	v_min_u32_e32 v33, v28, v30
	v_max_u32_e32 v28, v31, v1
	v_min_u32_e32 v29, v31, v1
	v_max_u32_e32 v30, v32, v2
	v_min_u32_e32 v31, v32, v2
	v_max_u32_e32 v32, v33, v0
	v_min_u32_e32 v33, v33, v0
	v_max_u32_e32 v0, v52, v51
	v_min_u32_e32 v1, v52, v51
	v_max_u32_e32 v2, v50, v37
	v_min_u32_e32 v34, v50, v37
	v_min_u32_e32 v36, v41, v45
	v_max_u32_e32 v37, v49, v3
	v_min_u32_e32 v3, v49, v3
	v_max_u32_e32 v38, v0, v2
	v_min_u32_e32 v0, v0, v2
	v_max_u32_e32 v2, v1, v34
	v_min_u32_e32 v1, v1, v34
	v_max_u32_e32 v39, v35, v37
	v_min_u32_e32 v34, v35, v37
	v_max_u32_e32 v35, v36, v3
	v_min_u32_e32 v3, v36, v3
	v_max_u32_e32 v36, v2, v0
	v_min_u32_e32 v0, v2, v0
	v_max_u32_e32 v2, v35, v34
	v_min_u32_e32 v35, v35, v34
	v_max_u32_e32 v34, v38, v39
	v_min_u32_e32 v37, v38, v39
	v_max_u32_e32 v38, v36, v2
	v_min_u32_e32 v2, v36, v2
	v_max_u32_e32 v36, v0, v35
	v_max_u32_e32 v39, v1, v3
	v_min_u32_e32 v0, v0, v35
	v_min_u32_e32 v35, v1, v3
	v_max_u32_e32 v1, v36, v37
	v_min_u32_e32 v3, v36, v37
	v_max_u32_e32 v40, v39, v2
	v_min_u32_e32 v2, v39, v2
	v_max_u32_e32 v36, v38, v1
	v_min_u32_e32 v37, v38, v1
	v_max_u32_e32 v38, v40, v3
	v_min_u32_e32 v39, v40, v3
	v_max_u32_e32 v40, v2, v0
	v_min_u32_e32 v41, v2, v0
	v_mov_b32_e32 v0, 0
	v_mov_b32_e32 v1, 0
	v_mov_b32_e32 v2, 0
	v_mov_b32_e32 v3, 0
.LBB0_1349:
	v_max_u32_dpp v43, v12, v12 row_ror:1 row_mask:0xf bank_mask:0xf bound_ctrl:1
	v_max_u32_dpp v42, v4, v4 row_ror:1 row_mask:0xf bank_mask:0xf bound_ctrl:1
	v_max_u32_dpp v44, v26, v26 row_ror:1 row_mask:0xf bank_mask:0xf bound_ctrl:1
	v_max_u32_dpp v43, v43, v43 row_ror:2 row_mask:0xf bank_mask:0xf bound_ctrl:1
	v_max_u32_dpp v45, v34, v34 row_ror:1 row_mask:0xf bank_mask:0xf bound_ctrl:1
	v_max_u32_dpp v42, v42, v42 row_ror:2 row_mask:0xf bank_mask:0xf bound_ctrl:1
	v_max_u32_dpp v44, v44, v44 row_ror:2 row_mask:0xf bank_mask:0xf bound_ctrl:1
	v_max_u32_dpp v43, v43, v43 row_ror:4 row_mask:0xf bank_mask:0xf bound_ctrl:1
	v_max_u32_dpp v45, v45, v45 row_ror:2 row_mask:0xf bank_mask:0xf bound_ctrl:1
	v_max_u32_dpp v42, v42, v42 row_ror:4 row_mask:0xf bank_mask:0xf bound_ctrl:1
	v_max_u32_dpp v44, v44, v44 row_ror:4 row_mask:0xf bank_mask:0xf bound_ctrl:1
	v_max_u32_dpp v43, v43, v43 row_ror:8 row_mask:0xf bank_mask:0xf bound_ctrl:1
	v_max_u32_dpp v45, v45, v45 row_ror:4 row_mask:0xf bank_mask:0xf bound_ctrl:1
	v_max_u32_dpp v42, v42, v42 row_ror:8 row_mask:0xf bank_mask:0xf bound_ctrl:1
	v_max_u32_dpp v44, v44, v44 row_ror:8 row_mask:0xf bank_mask:0xf bound_ctrl:1
	v_cmp_eq_u32_e64 s[0:1], v12, v43
	v_max_u32_dpp v45, v45, v45 row_ror:8 row_mask:0xf bank_mask:0xf bound_ctrl:1
	v_cmp_eq_u32_e32 vcc, v4, v42
	v_cndmask_b32_e64 v12, v12, v14, s[0:1]
	v_cndmask_b32_e64 v14, v14, v15, s[0:1]
	v_cndmask_b32_e64 v15, v15, v22, s[0:1]
	v_cndmask_b32_e64 v22, v22, v23, s[0:1]
	v_cndmask_b32_e64 v23, v23, v24, s[0:1]
	v_cndmask_b32_e64 v24, v24, v25, s[0:1]
	v_cndmask_b32_e64 v25, v25, v13, s[0:1]
	v_cndmask_b32_e64 v13, v13, 0, s[0:1]
	v_cmp_eq_u32_e64 s[0:1], v26, v44
	v_cndmask_b32_e32 v4, v4, v6, vcc
	v_cndmask_b32_e32 v6, v6, v7, vcc
	v_cndmask_b32_e32 v7, v7, v8, vcc
	v_cndmask_b32_e32 v8, v8, v9, vcc
	v_cndmask_b32_e32 v9, v9, v10, vcc
	v_cndmask_b32_e32 v10, v10, v11, vcc
	v_cndmask_b32_e32 v11, v11, v5, vcc
	v_cndmask_b32_e64 v5, v5, 0, vcc
	s_lshl_b64 vcc, s[78:79], s40
	v_cndmask_b32_e64 v26, v26, v28, s[0:1]
	v_cndmask_b32_e64 v28, v28, v29, s[0:1]
	v_cndmask_b32_e64 v29, v29, v30, s[0:1]
	v_cndmask_b32_e64 v30, v30, v31, s[0:1]
	v_cndmask_b32_e64 v31, v31, v32, s[0:1]
	v_cndmask_b32_e64 v32, v32, v33, s[0:1]
	v_cndmask_b32_e64 v33, v33, v27, s[0:1]
	v_cndmask_b32_e64 v27, v27, 0, s[0:1]
	v_cmp_eq_u32_e64 s[0:1], v34, v45
	s_add_i32 s40, s40, 1
	v_cndmask_b32_e32 v0, v0, v42, vcc
	v_cndmask_b32_e32 v1, v1, v43, vcc
	v_cndmask_b32_e32 v2, v2, v44, vcc
	v_cndmask_b32_e64 v34, v34, v36, s[0:1]
	v_cndmask_b32_e64 v36, v36, v37, s[0:1]
	v_cndmask_b32_e64 v37, v37, v38, s[0:1]
	v_cndmask_b32_e64 v38, v38, v39, s[0:1]
	v_cndmask_b32_e64 v39, v39, v40, s[0:1]
	v_cndmask_b32_e64 v40, v40, v41, s[0:1]
	v_cndmask_b32_e64 v41, v41, v35, s[0:1]
	v_cndmask_b32_e64 v35, v35, 0, s[0:1]
	s_cmp_lg_u32 s40, 8
	v_cndmask_b32_e32 v3, v3, v45, vcc
	s_cbranch_scc1 .LBB0_1349
	v_max_u32_dpp v43, v12, v12 row_ror:1 row_mask:0xf bank_mask:0xf bound_ctrl:1
	v_max_u32_dpp v42, v4, v4 row_ror:1 row_mask:0xf bank_mask:0xf bound_ctrl:1
	v_max_u32_dpp v44, v26, v26 row_ror:1 row_mask:0xf bank_mask:0xf bound_ctrl:1
	v_max_u32_dpp v43, v43, v43 row_ror:2 row_mask:0xf bank_mask:0xf bound_ctrl:1
	v_max_u32_dpp v45, v34, v34 row_ror:1 row_mask:0xf bank_mask:0xf bound_ctrl:1
	v_max_u32_dpp v42, v42, v42 row_ror:2 row_mask:0xf bank_mask:0xf bound_ctrl:1
	v_max_u32_dpp v44, v44, v44 row_ror:2 row_mask:0xf bank_mask:0xf bound_ctrl:1
	v_max_u32_dpp v43, v43, v43 row_ror:4 row_mask:0xf bank_mask:0xf bound_ctrl:1
	v_max_u32_dpp v45, v45, v45 row_ror:2 row_mask:0xf bank_mask:0xf bound_ctrl:1
	v_max_u32_dpp v42, v42, v42 row_ror:4 row_mask:0xf bank_mask:0xf bound_ctrl:1
	v_max_u32_dpp v44, v44, v44 row_ror:4 row_mask:0xf bank_mask:0xf bound_ctrl:1
	v_max_u32_dpp v43, v43, v43 row_ror:8 row_mask:0xf bank_mask:0xf bound_ctrl:1
	v_max_u32_dpp v45, v45, v45 row_ror:4 row_mask:0xf bank_mask:0xf bound_ctrl:1
	v_max_u32_dpp v42, v42, v42 row_ror:8 row_mask:0xf bank_mask:0xf bound_ctrl:1
	v_max_u32_dpp v44, v44, v44 row_ror:8 row_mask:0xf bank_mask:0xf bound_ctrl:1
	v_cmp_eq_u32_e64 s[0:1], v12, v43
	v_max_u32_dpp v45, v45, v45 row_ror:8 row_mask:0xf bank_mask:0xf bound_ctrl:1
	v_cmp_eq_u32_e32 vcc, v4, v42
	v_cndmask_b32_e64 v12, v12, v14, s[0:1]
	v_cndmask_b32_e64 v14, v14, v15, s[0:1]
	v_cndmask_b32_e64 v15, v15, v22, s[0:1]
	v_cndmask_b32_e64 v22, v22, v23, s[0:1]
	v_cndmask_b32_e64 v23, v23, v24, s[0:1]
	v_cndmask_b32_e64 v24, v24, v25, s[0:1]
	v_cndmask_b32_e64 v25, v25, v13, s[0:1]
	v_cmp_eq_u32_e64 s[0:1], v26, v44
	v_cndmask_b32_e32 v4, v4, v6, vcc
	v_cndmask_b32_e32 v6, v6, v7, vcc
	v_cndmask_b32_e32 v7, v7, v8, vcc
	v_cndmask_b32_e32 v8, v8, v9, vcc
	v_cndmask_b32_e32 v9, v9, v10, vcc
	v_cndmask_b32_e32 v10, v10, v11, vcc
	v_cndmask_b32_e32 v11, v11, v5, vcc
	s_lshl_b64 vcc, s[78:79], s40
	v_cndmask_b32_e64 v26, v26, v28, s[0:1]
	v_cndmask_b32_e64 v28, v28, v29, s[0:1]
	v_cndmask_b32_e64 v29, v29, v30, s[0:1]
	v_cndmask_b32_e64 v30, v30, v31, s[0:1]
	v_cndmask_b32_e64 v31, v31, v32, s[0:1]
	v_cndmask_b32_e64 v32, v32, v33, s[0:1]
	v_cndmask_b32_e64 v33, v33, v27, s[0:1]
	v_cmp_eq_u32_e64 s[0:1], v34, v45
	s_add_i32 s40, s40, 1
	v_cndmask_b32_e32 v0, v0, v42, vcc
	v_cndmask_b32_e32 v1, v1, v43, vcc
	v_cndmask_b32_e32 v2, v2, v44, vcc
	v_cndmask_b32_e64 v34, v34, v36, s[0:1]
	v_cndmask_b32_e64 v36, v36, v37, s[0:1]
	v_cndmask_b32_e64 v37, v37, v38, s[0:1]
	v_cndmask_b32_e64 v38, v38, v39, s[0:1]
	v_cndmask_b32_e64 v39, v39, v40, s[0:1]
	v_cndmask_b32_e64 v40, v40, v41, s[0:1]
	v_cndmask_b32_e64 v41, v41, v35, s[0:1]
	v_cndmask_b32_e32 v3, v3, v45, vcc
	v_max_u32_dpp v43, v12, v12 row_ror:1 row_mask:0xf bank_mask:0xf bound_ctrl:1
	v_max_u32_dpp v42, v4, v4 row_ror:1 row_mask:0xf bank_mask:0xf bound_ctrl:1
	v_max_u32_dpp v44, v26, v26 row_ror:1 row_mask:0xf bank_mask:0xf bound_ctrl:1
	v_max_u32_dpp v43, v43, v43 row_ror:2 row_mask:0xf bank_mask:0xf bound_ctrl:1
	v_max_u32_dpp v45, v34, v34 row_ror:1 row_mask:0xf bank_mask:0xf bound_ctrl:1
	v_max_u32_dpp v42, v42, v42 row_ror:2 row_mask:0xf bank_mask:0xf bound_ctrl:1
	v_max_u32_dpp v44, v44, v44 row_ror:2 row_mask:0xf bank_mask:0xf bound_ctrl:1
	v_max_u32_dpp v43, v43, v43 row_ror:4 row_mask:0xf bank_mask:0xf bound_ctrl:1
	v_max_u32_dpp v45, v45, v45 row_ror:2 row_mask:0xf bank_mask:0xf bound_ctrl:1
	v_max_u32_dpp v42, v42, v42 row_ror:4 row_mask:0xf bank_mask:0xf bound_ctrl:1
	v_max_u32_dpp v44, v44, v44 row_ror:4 row_mask:0xf bank_mask:0xf bound_ctrl:1
	v_max_u32_dpp v43, v43, v43 row_ror:8 row_mask:0xf bank_mask:0xf bound_ctrl:1
	v_max_u32_dpp v45, v45, v45 row_ror:4 row_mask:0xf bank_mask:0xf bound_ctrl:1
	v_max_u32_dpp v42, v42, v42 row_ror:8 row_mask:0xf bank_mask:0xf bound_ctrl:1
	v_max_u32_dpp v44, v44, v44 row_ror:8 row_mask:0xf bank_mask:0xf bound_ctrl:1
	v_cmp_eq_u32_e64 s[0:1], v12, v43
	v_max_u32_dpp v45, v45, v45 row_ror:8 row_mask:0xf bank_mask:0xf bound_ctrl:1
	v_cmp_eq_u32_e32 vcc, v4, v42
	v_cndmask_b32_e64 v12, v12, v14, s[0:1]
	v_cndmask_b32_e64 v14, v14, v15, s[0:1]
	v_cndmask_b32_e64 v15, v15, v22, s[0:1]
	v_cndmask_b32_e64 v22, v22, v23, s[0:1]
	v_cndmask_b32_e64 v23, v23, v24, s[0:1]
	v_cndmask_b32_e64 v24, v24, v25, s[0:1]
	v_cmp_eq_u32_e64 s[0:1], v26, v44
	v_cndmask_b32_e32 v4, v4, v6, vcc
	v_cndmask_b32_e32 v6, v6, v7, vcc
	v_cndmask_b32_e32 v7, v7, v8, vcc
	v_cndmask_b32_e32 v8, v8, v9, vcc
	v_cndmask_b32_e32 v9, v9, v10, vcc
	v_cndmask_b32_e32 v10, v10, v11, vcc
	s_lshl_b64 vcc, s[78:79], s40
	v_cndmask_b32_e64 v26, v26, v28, s[0:1]
	v_cndmask_b32_e64 v28, v28, v29, s[0:1]
	v_cndmask_b32_e64 v29, v29, v30, s[0:1]
	v_cndmask_b32_e64 v30, v30, v31, s[0:1]
	v_cndmask_b32_e64 v31, v31, v32, s[0:1]
	v_cndmask_b32_e64 v32, v32, v33, s[0:1]
	v_cmp_eq_u32_e64 s[0:1], v34, v45
	s_add_i32 s40, s40, 1
	v_cndmask_b32_e32 v0, v0, v42, vcc
	v_cndmask_b32_e32 v1, v1, v43, vcc
	v_cndmask_b32_e32 v2, v2, v44, vcc
	v_cndmask_b32_e64 v34, v34, v36, s[0:1]
	v_cndmask_b32_e64 v36, v36, v37, s[0:1]
	v_cndmask_b32_e64 v37, v37, v38, s[0:1]
	v_cndmask_b32_e64 v38, v38, v39, s[0:1]
	v_cndmask_b32_e64 v39, v39, v40, s[0:1]
	v_cndmask_b32_e64 v40, v40, v41, s[0:1]
	v_cndmask_b32_e32 v3, v3, v45, vcc
	v_max_u32_dpp v43, v12, v12 row_ror:1 row_mask:0xf bank_mask:0xf bound_ctrl:1
	v_max_u32_dpp v42, v4, v4 row_ror:1 row_mask:0xf bank_mask:0xf bound_ctrl:1
	v_max_u32_dpp v44, v26, v26 row_ror:1 row_mask:0xf bank_mask:0xf bound_ctrl:1
	v_max_u32_dpp v43, v43, v43 row_ror:2 row_mask:0xf bank_mask:0xf bound_ctrl:1
	v_max_u32_dpp v45, v34, v34 row_ror:1 row_mask:0xf bank_mask:0xf bound_ctrl:1
	v_max_u32_dpp v42, v42, v42 row_ror:2 row_mask:0xf bank_mask:0xf bound_ctrl:1
	v_max_u32_dpp v44, v44, v44 row_ror:2 row_mask:0xf bank_mask:0xf bound_ctrl:1
	v_max_u32_dpp v43, v43, v43 row_ror:4 row_mask:0xf bank_mask:0xf bound_ctrl:1
	v_max_u32_dpp v45, v45, v45 row_ror:2 row_mask:0xf bank_mask:0xf bound_ctrl:1
	v_max_u32_dpp v42, v42, v42 row_ror:4 row_mask:0xf bank_mask:0xf bound_ctrl:1
	v_max_u32_dpp v44, v44, v44 row_ror:4 row_mask:0xf bank_mask:0xf bound_ctrl:1
	v_max_u32_dpp v43, v43, v43 row_ror:8 row_mask:0xf bank_mask:0xf bound_ctrl:1
	v_max_u32_dpp v45, v45, v45 row_ror:4 row_mask:0xf bank_mask:0xf bound_ctrl:1
	v_max_u32_dpp v42, v42, v42 row_ror:8 row_mask:0xf bank_mask:0xf bound_ctrl:1
	v_max_u32_dpp v44, v44, v44 row_ror:8 row_mask:0xf bank_mask:0xf bound_ctrl:1
	v_cmp_eq_u32_e64 s[0:1], v12, v43
	v_max_u32_dpp v45, v45, v45 row_ror:8 row_mask:0xf bank_mask:0xf bound_ctrl:1
	v_cmp_eq_u32_e32 vcc, v4, v42
	v_cndmask_b32_e64 v12, v12, v14, s[0:1]
	v_cndmask_b32_e64 v14, v14, v15, s[0:1]
	v_cndmask_b32_e64 v15, v15, v22, s[0:1]
	v_cndmask_b32_e64 v22, v22, v23, s[0:1]
	v_cndmask_b32_e64 v23, v23, v24, s[0:1]
	v_cmp_eq_u32_e64 s[0:1], v26, v44
	v_cndmask_b32_e32 v4, v4, v6, vcc
	v_cndmask_b32_e32 v6, v6, v7, vcc
	v_cndmask_b32_e32 v7, v7, v8, vcc
	v_cndmask_b32_e32 v8, v8, v9, vcc
	v_cndmask_b32_e32 v9, v9, v10, vcc
	s_lshl_b64 vcc, s[78:79], s40
	v_cndmask_b32_e64 v26, v26, v28, s[0:1]
	v_cndmask_b32_e64 v28, v28, v29, s[0:1]
	v_cndmask_b32_e64 v29, v29, v30, s[0:1]
	v_cndmask_b32_e64 v30, v30, v31, s[0:1]
	v_cndmask_b32_e64 v31, v31, v32, s[0:1]
	v_cmp_eq_u32_e64 s[0:1], v34, v45
	s_add_i32 s40, s40, 1
	v_cndmask_b32_e32 v0, v0, v42, vcc
	v_cndmask_b32_e32 v1, v1, v43, vcc
	v_cndmask_b32_e32 v2, v2, v44, vcc
	v_cndmask_b32_e64 v34, v34, v36, s[0:1]
	v_cndmask_b32_e64 v36, v36, v37, s[0:1]
	v_cndmask_b32_e64 v37, v37, v38, s[0:1]
	v_cndmask_b32_e64 v38, v38, v39, s[0:1]
	v_cndmask_b32_e64 v39, v39, v40, s[0:1]
	v_cndmask_b32_e32 v3, v3, v45, vcc
	v_max_u32_dpp v43, v12, v12 row_ror:1 row_mask:0xf bank_mask:0xf bound_ctrl:1
	v_max_u32_dpp v42, v4, v4 row_ror:1 row_mask:0xf bank_mask:0xf bound_ctrl:1
	v_max_u32_dpp v44, v26, v26 row_ror:1 row_mask:0xf bank_mask:0xf bound_ctrl:1
	v_max_u32_dpp v43, v43, v43 row_ror:2 row_mask:0xf bank_mask:0xf bound_ctrl:1
	v_max_u32_dpp v45, v34, v34 row_ror:1 row_mask:0xf bank_mask:0xf bound_ctrl:1
	v_max_u32_dpp v42, v42, v42 row_ror:2 row_mask:0xf bank_mask:0xf bound_ctrl:1
	v_max_u32_dpp v44, v44, v44 row_ror:2 row_mask:0xf bank_mask:0xf bound_ctrl:1
	v_max_u32_dpp v43, v43, v43 row_ror:4 row_mask:0xf bank_mask:0xf bound_ctrl:1
	v_max_u32_dpp v45, v45, v45 row_ror:2 row_mask:0xf bank_mask:0xf bound_ctrl:1
	v_max_u32_dpp v42, v42, v42 row_ror:4 row_mask:0xf bank_mask:0xf bound_ctrl:1
	v_max_u32_dpp v44, v44, v44 row_ror:4 row_mask:0xf bank_mask:0xf bound_ctrl:1
	v_max_u32_dpp v43, v43, v43 row_ror:8 row_mask:0xf bank_mask:0xf bound_ctrl:1
	v_max_u32_dpp v45, v45, v45 row_ror:4 row_mask:0xf bank_mask:0xf bound_ctrl:1
	v_max_u32_dpp v42, v42, v42 row_ror:8 row_mask:0xf bank_mask:0xf bound_ctrl:1
	v_max_u32_dpp v44, v44, v44 row_ror:8 row_mask:0xf bank_mask:0xf bound_ctrl:1
	v_cmp_eq_u32_e64 s[0:1], v12, v43
	v_max_u32_dpp v45, v45, v45 row_ror:8 row_mask:0xf bank_mask:0xf bound_ctrl:1
	v_cmp_eq_u32_e32 vcc, v4, v42
	v_cndmask_b32_e64 v12, v12, v14, s[0:1]
	v_cndmask_b32_e64 v14, v14, v15, s[0:1]
	v_cndmask_b32_e64 v15, v15, v22, s[0:1]
	v_cndmask_b32_e64 v22, v22, v23, s[0:1]
	v_cmp_eq_u32_e64 s[0:1], v26, v44
	v_cndmask_b32_e32 v4, v4, v6, vcc
	v_cndmask_b32_e32 v6, v6, v7, vcc
	v_cndmask_b32_e32 v7, v7, v8, vcc
	v_cndmask_b32_e32 v8, v8, v9, vcc
	s_lshl_b64 vcc, s[78:79], s40
	v_cndmask_b32_e64 v26, v26, v28, s[0:1]
	v_cndmask_b32_e64 v28, v28, v29, s[0:1]
	v_cndmask_b32_e64 v29, v29, v30, s[0:1]
	v_cndmask_b32_e64 v30, v30, v31, s[0:1]
	v_cmp_eq_u32_e64 s[0:1], v34, v45
	s_add_i32 s40, s40, 1
	v_cndmask_b32_e32 v0, v0, v42, vcc
	v_cndmask_b32_e32 v1, v1, v43, vcc
	v_cndmask_b32_e32 v2, v2, v44, vcc
	v_cndmask_b32_e64 v34, v34, v36, s[0:1]
	v_cndmask_b32_e64 v36, v36, v37, s[0:1]
	v_cndmask_b32_e64 v37, v37, v38, s[0:1]
	v_cndmask_b32_e64 v38, v38, v39, s[0:1]
	v_cndmask_b32_e32 v3, v3, v45, vcc
	v_max_u32_dpp v43, v12, v12 row_ror:1 row_mask:0xf bank_mask:0xf bound_ctrl:1
	v_max_u32_dpp v42, v4, v4 row_ror:1 row_mask:0xf bank_mask:0xf bound_ctrl:1
	v_max_u32_dpp v44, v26, v26 row_ror:1 row_mask:0xf bank_mask:0xf bound_ctrl:1
	v_max_u32_dpp v43, v43, v43 row_ror:2 row_mask:0xf bank_mask:0xf bound_ctrl:1
	v_max_u32_dpp v45, v34, v34 row_ror:1 row_mask:0xf bank_mask:0xf bound_ctrl:1
	v_max_u32_dpp v42, v42, v42 row_ror:2 row_mask:0xf bank_mask:0xf bound_ctrl:1
	v_max_u32_dpp v44, v44, v44 row_ror:2 row_mask:0xf bank_mask:0xf bound_ctrl:1
	v_max_u32_dpp v43, v43, v43 row_ror:4 row_mask:0xf bank_mask:0xf bound_ctrl:1
	v_max_u32_dpp v45, v45, v45 row_ror:2 row_mask:0xf bank_mask:0xf bound_ctrl:1
	v_max_u32_dpp v42, v42, v42 row_ror:4 row_mask:0xf bank_mask:0xf bound_ctrl:1
	v_max_u32_dpp v44, v44, v44 row_ror:4 row_mask:0xf bank_mask:0xf bound_ctrl:1
	v_max_u32_dpp v43, v43, v43 row_ror:8 row_mask:0xf bank_mask:0xf bound_ctrl:1
	v_max_u32_dpp v45, v45, v45 row_ror:4 row_mask:0xf bank_mask:0xf bound_ctrl:1
	v_max_u32_dpp v42, v42, v42 row_ror:8 row_mask:0xf bank_mask:0xf bound_ctrl:1
	v_max_u32_dpp v44, v44, v44 row_ror:8 row_mask:0xf bank_mask:0xf bound_ctrl:1
	v_cmp_eq_u32_e64 s[0:1], v12, v43
	v_max_u32_dpp v45, v45, v45 row_ror:8 row_mask:0xf bank_mask:0xf bound_ctrl:1
	v_cmp_eq_u32_e32 vcc, v4, v42
	v_cndmask_b32_e64 v12, v12, v14, s[0:1]
	v_cndmask_b32_e64 v14, v14, v15, s[0:1]
	v_cndmask_b32_e64 v15, v15, v22, s[0:1]
	v_cmp_eq_u32_e64 s[0:1], v26, v44
	v_cndmask_b32_e32 v4, v4, v6, vcc
	v_cndmask_b32_e32 v6, v6, v7, vcc
	v_cndmask_b32_e32 v7, v7, v8, vcc
	s_lshl_b64 vcc, s[78:79], s40
	v_cndmask_b32_e64 v26, v26, v28, s[0:1]
	v_cndmask_b32_e64 v28, v28, v29, s[0:1]
	v_cndmask_b32_e64 v29, v29, v30, s[0:1]
	v_cmp_eq_u32_e64 s[0:1], v34, v45
	s_add_i32 s40, s40, 1
	v_cndmask_b32_e32 v0, v0, v42, vcc
	v_cndmask_b32_e32 v1, v1, v43, vcc
	v_cndmask_b32_e32 v2, v2, v44, vcc
	v_cndmask_b32_e64 v34, v34, v36, s[0:1]
	v_cndmask_b32_e64 v36, v36, v37, s[0:1]
	v_cndmask_b32_e64 v37, v37, v38, s[0:1]
	v_cndmask_b32_e32 v3, v3, v45, vcc
	v_max_u32_dpp v43, v12, v12 row_ror:1 row_mask:0xf bank_mask:0xf bound_ctrl:1
	v_max_u32_dpp v42, v4, v4 row_ror:1 row_mask:0xf bank_mask:0xf bound_ctrl:1
	v_max_u32_dpp v44, v26, v26 row_ror:1 row_mask:0xf bank_mask:0xf bound_ctrl:1
	v_max_u32_dpp v43, v43, v43 row_ror:2 row_mask:0xf bank_mask:0xf bound_ctrl:1
	v_max_u32_dpp v45, v34, v34 row_ror:1 row_mask:0xf bank_mask:0xf bound_ctrl:1
	v_max_u32_dpp v42, v42, v42 row_ror:2 row_mask:0xf bank_mask:0xf bound_ctrl:1
	v_max_u32_dpp v44, v44, v44 row_ror:2 row_mask:0xf bank_mask:0xf bound_ctrl:1
	v_max_u32_dpp v43, v43, v43 row_ror:4 row_mask:0xf bank_mask:0xf bound_ctrl:1
	v_max_u32_dpp v45, v45, v45 row_ror:2 row_mask:0xf bank_mask:0xf bound_ctrl:1
	v_max_u32_dpp v42, v42, v42 row_ror:4 row_mask:0xf bank_mask:0xf bound_ctrl:1
	v_max_u32_dpp v44, v44, v44 row_ror:4 row_mask:0xf bank_mask:0xf bound_ctrl:1
	v_max_u32_dpp v43, v43, v43 row_ror:8 row_mask:0xf bank_mask:0xf bound_ctrl:1
	v_max_u32_dpp v45, v45, v45 row_ror:4 row_mask:0xf bank_mask:0xf bound_ctrl:1
	v_max_u32_dpp v42, v42, v42 row_ror:8 row_mask:0xf bank_mask:0xf bound_ctrl:1
	v_max_u32_dpp v44, v44, v44 row_ror:8 row_mask:0xf bank_mask:0xf bound_ctrl:1
	v_cmp_eq_u32_e64 s[0:1], v12, v43
	v_max_u32_dpp v45, v45, v45 row_ror:8 row_mask:0xf bank_mask:0xf bound_ctrl:1
	v_cmp_eq_u32_e32 vcc, v4, v42
	v_cndmask_b32_e64 v12, v12, v14, s[0:1]
	v_cndmask_b32_e64 v14, v14, v15, s[0:1]
	v_cmp_eq_u32_e64 s[0:1], v26, v44
	v_cndmask_b32_e32 v4, v4, v6, vcc
	v_cndmask_b32_e32 v6, v6, v7, vcc
	s_lshl_b64 vcc, s[78:79], s40
	v_cndmask_b32_e64 v26, v26, v28, s[0:1]
	v_cndmask_b32_e64 v28, v28, v29, s[0:1]
	v_cmp_eq_u32_e64 s[0:1], v34, v45
	s_add_i32 s40, s40, 1
	v_cndmask_b32_e32 v0, v0, v42, vcc
	v_cndmask_b32_e32 v1, v1, v43, vcc
	v_cndmask_b32_e32 v2, v2, v44, vcc
	v_cndmask_b32_e64 v34, v34, v36, s[0:1]
	v_cndmask_b32_e64 v36, v36, v37, s[0:1]
	v_cndmask_b32_e32 v3, v3, v45, vcc
	v_max_u32_dpp v43, v12, v12 row_ror:1 row_mask:0xf bank_mask:0xf bound_ctrl:1
	v_max_u32_dpp v42, v4, v4 row_ror:1 row_mask:0xf bank_mask:0xf bound_ctrl:1
	v_max_u32_dpp v44, v26, v26 row_ror:1 row_mask:0xf bank_mask:0xf bound_ctrl:1
	v_max_u32_dpp v43, v43, v43 row_ror:2 row_mask:0xf bank_mask:0xf bound_ctrl:1
	v_max_u32_dpp v45, v34, v34 row_ror:1 row_mask:0xf bank_mask:0xf bound_ctrl:1
	v_max_u32_dpp v42, v42, v42 row_ror:2 row_mask:0xf bank_mask:0xf bound_ctrl:1
	v_max_u32_dpp v44, v44, v44 row_ror:2 row_mask:0xf bank_mask:0xf bound_ctrl:1
	v_max_u32_dpp v43, v43, v43 row_ror:4 row_mask:0xf bank_mask:0xf bound_ctrl:1
	v_max_u32_dpp v45, v45, v45 row_ror:2 row_mask:0xf bank_mask:0xf bound_ctrl:1
	v_max_u32_dpp v42, v42, v42 row_ror:4 row_mask:0xf bank_mask:0xf bound_ctrl:1
	v_max_u32_dpp v44, v44, v44 row_ror:4 row_mask:0xf bank_mask:0xf bound_ctrl:1
	v_max_u32_dpp v43, v43, v43 row_ror:8 row_mask:0xf bank_mask:0xf bound_ctrl:1
	v_max_u32_dpp v45, v45, v45 row_ror:4 row_mask:0xf bank_mask:0xf bound_ctrl:1
	v_max_u32_dpp v42, v42, v42 row_ror:8 row_mask:0xf bank_mask:0xf bound_ctrl:1
	v_max_u32_dpp v44, v44, v44 row_ror:8 row_mask:0xf bank_mask:0xf bound_ctrl:1
	v_cmp_eq_u32_e64 s[0:1], v12, v43
	v_max_u32_dpp v45, v45, v45 row_ror:8 row_mask:0xf bank_mask:0xf bound_ctrl:1
	v_cmp_eq_u32_e32 vcc, v4, v42
	v_cndmask_b32_e64 v12, v12, v14, s[0:1]
	v_cmp_eq_u32_e64 s[0:1], v26, v44
	v_cndmask_b32_e32 v4, v4, v6, vcc
	s_lshl_b64 vcc, s[78:79], s40
	v_cndmask_b32_e64 v26, v26, v28, s[0:1]
	v_cmp_eq_u32_e64 s[0:1], v34, v45
	s_add_i32 s40, s40, 1
	v_cndmask_b32_e32 v0, v0, v42, vcc
	v_cndmask_b32_e32 v1, v1, v43, vcc
	v_cndmask_b32_e32 v2, v2, v44, vcc
	v_cndmask_b32_e64 v34, v34, v36, s[0:1]
	v_cndmask_b32_e32 v3, v3, v45, vcc
	v_max_u32_dpp v43, v12, v12 row_ror:1 row_mask:0xf bank_mask:0xf bound_ctrl:1
	v_max_u32_dpp v42, v4, v4 row_ror:1 row_mask:0xf bank_mask:0xf bound_ctrl:1
	v_max_u32_dpp v44, v26, v26 row_ror:1 row_mask:0xf bank_mask:0xf bound_ctrl:1
	v_max_u32_dpp v43, v43, v43 row_ror:2 row_mask:0xf bank_mask:0xf bound_ctrl:1
	v_max_u32_dpp v45, v34, v34 row_ror:1 row_mask:0xf bank_mask:0xf bound_ctrl:1
	v_max_u32_dpp v42, v42, v42 row_ror:2 row_mask:0xf bank_mask:0xf bound_ctrl:1
	v_max_u32_dpp v44, v44, v44 row_ror:2 row_mask:0xf bank_mask:0xf bound_ctrl:1
	v_max_u32_dpp v43, v43, v43 row_ror:4 row_mask:0xf bank_mask:0xf bound_ctrl:1
	v_max_u32_dpp v45, v45, v45 row_ror:2 row_mask:0xf bank_mask:0xf bound_ctrl:1
	v_max_u32_dpp v42, v42, v42 row_ror:4 row_mask:0xf bank_mask:0xf bound_ctrl:1
	v_max_u32_dpp v44, v44, v44 row_ror:4 row_mask:0xf bank_mask:0xf bound_ctrl:1
	v_max_u32_dpp v43, v43, v43 row_ror:8 row_mask:0xf bank_mask:0xf bound_ctrl:1
	v_max_u32_dpp v45, v45, v45 row_ror:4 row_mask:0xf bank_mask:0xf bound_ctrl:1
	v_max_u32_dpp v42, v42, v42 row_ror:8 row_mask:0xf bank_mask:0xf bound_ctrl:1
	v_max_u32_dpp v44, v44, v44 row_ror:8 row_mask:0xf bank_mask:0xf bound_ctrl:1
	v_max_u32_dpp v45, v45, v45 row_ror:8 row_mask:0xf bank_mask:0xf bound_ctrl:1
	s_lshl_b64 vcc, s[78:79], s40
	v_cndmask_b32_e32 v0, v0, v42, vcc
	v_cndmask_b32_e32 v1, v1, v43, vcc
	v_cndmask_b32_e32 v2, v2, v44, vcc
	v_cndmask_b32_e32 v3, v3, v45, vcc
	v_cmp_lt_i32_e32 vcc, -1, v18
	v_mov_b32_e32 v6, 0
	v_mov_b32_e32 v7, 0
	v_cndmask_b32_e64 v4, v217, -1, vcc
	v_cmp_lt_i32_e32 vcc, -1, v0
	v_bitop3_b32 v8, v4, v18, s67 bitop3:0x78
	ds_bpermute_b32 v10, v198, v8
	v_cndmask_b32_e64 v4, v217, -1, vcc
	v_bitop3_b32 v9, v4, v0, s67 bitop3:0x78
	ds_bpermute_b32 v4, v196, v8
	ds_bpermute_b32 v5, v197, v9
	ds_bpermute_b32 v11, v199, v9
	s_and_saveexec_b64 s[0:1], s[6:7]
	s_cbranch_execz .LBB0_1352
	s_waitcnt lgkmcnt(0)
	v_add_f32_e32 v7, v10, v11
	v_cmp_lt_i32_e32 vcc, -1, v7
	s_nop 1
	v_cndmask_b32_e32 v10, -1, v217, vcc
	v_bitop3_b32 v7, v10, s59, v7 bitop3:0x48
	v_bitop3_b32 v7, v7, s54, v172 bitop3:0x36

.LBB0_1374:
	s_or_b64 exec, exec, s[0:1]
	v_add_f32_e32 v25, v25, v29
	v_cmp_lt_i32_e32 vcc, -1, v25
	v_add_f32_e32 v22, v22, v23
	v_add_f32_e32 v10, v10, v11
	v_cndmask_b32_e32 v29, -1, v217, vcc
	v_cmp_lt_i32_e32 vcc, -1, v22
	v_add_f32_e32 v4, v4, v5
	v_bitop3_b32 v25, v29, s59, v25 bitop3:0x48
	v_cndmask_b32_e32 v23, -1, v217, vcc
	v_cmp_lt_i32_e32 vcc, -1, v10
	v_bitop3_b32 v22, v23, s59, v22 bitop3:0x48
	v_bitop3_b32 v29, v25, s54, v174 bitop3:0x36
	v_cndmask_b32_e32 v11, -1, v217, vcc
	v_cmp_lt_i32_e32 vcc, -1, v4
	v_bitop3_b32 v10, v11, s59, v10 bitop3:0x48
	v_bitop3_b32 v23, v10, s54, v174 bitop3:0x36
	v_cndmask_b32_e32 v5, -1, v217, vcc
	v_bitop3_b32 v4, v5, s59, v4 bitop3:0x48
	v_bitop3_b32 v4, v4, s54, v174 bitop3:0x36
	v_max_u32_e32 v5, v4, v7
	v_min_u32_e32 v4, v4, v7
	v_max_u32_e32 v7, v6, v9
	v_min_u32_e32 v6, v6, v9
	v_max_u32_e32 v9, v5, v7
	v_min_u32_e32 v5, v5, v7
	v_max_u32_e32 v7, v4, v6
	v_bitop3_b32 v25, v22, s54, v174 bitop3:0x36
	v_min_u32_e32 v10, v4, v6
	v_max_u32_e32 v11, v7, v5
	v_min_u32_e32 v22, v7, v5
	v_max_u32_e32 v4, v23, v8
	v_min_u32_e32 v5, v23, v8
	v_max_u32_e32 v6, v13, v12
	v_min_u32_e32 v7, v13, v12
	v_max_u32_e32 v8, v4, v6
	v_min_u32_e32 v4, v4, v6
	v_max_u32_e32 v6, v5, v7
	v_min_u32_e32 v12, v5, v7
	v_max_u32_e32 v13, v6, v4
	v_min_u32_e32 v23, v6, v4
	v_max_u32_e32 v4, v25, v15
	v_min_u32_e32 v5, v25, v15
	v_max_u32_e32 v6, v14, v24
	v_min_u32_e32 v7, v14, v24
	v_max_u32_e32 v14, v4, v6
	v_min_u32_e32 v4, v4, v6
	v_max_u32_e32 v6, v5, v7
	v_min_u32_e32 v15, v5, v7
	v_max_u32_e32 v24, v6, v4
	v_min_u32_e32 v25, v6, v4
	v_max_u32_e32 v4, v29, v26
	v_min_u32_e32 v5, v29, v26
	v_max_u32_e32 v6, v28, v27
	v_min_u32_e32 v7, v28, v27
	v_max_u32_e32 v26, v4, v6
	v_min_u32_e32 v4, v4, v6
	v_max_u32_e32 v6, v5, v7
	v_min_u32_e32 v27, v5, v7
	v_max_u32_e32 v28, v6, v4
	v_min_u32_e32 v29, v6, v4
	s_mov_b32 s40, 0
	v_mov_b32_e32 v7, 0
	v_mov_b32_e32 v6, 0
	v_mov_b32_e32 v5, 0
	v_mov_b32_e32 v4, 0
	s_waitcnt lgkmcnt(0)
.LBB0_1375:
	v_max_u32_dpp v31, v8, v8 row_ror:1 row_mask:0xf bank_mask:0xf bound_ctrl:1
	v_max_u32_dpp v30, v9, v9 row_ror:1 row_mask:0xf bank_mask:0xf bound_ctrl:1
	v_max_u32_dpp v32, v14, v14 row_ror:1 row_mask:0xf bank_mask:0xf bound_ctrl:1
	v_max_u32_dpp v31, v31, v31 row_ror:2 row_mask:0xf bank_mask:0xf bound_ctrl:1
	v_max_u32_dpp v33, v26, v26 row_ror:1 row_mask:0xf bank_mask:0xf bound_ctrl:1
	v_max_u32_dpp v30, v30, v30 row_ror:2 row_mask:0xf bank_mask:0xf bound_ctrl:1
	v_max_u32_dpp v32, v32, v32 row_ror:2 row_mask:0xf bank_mask:0xf bound_ctrl:1
	v_max_u32_dpp v31, v31, v31 row_ror:4 row_mask:0xf bank_mask:0xf bound_ctrl:1
	v_max_u32_dpp v33, v33, v33 row_ror:2 row_mask:0xf bank_mask:0xf bound_ctrl:1
	v_max_u32_dpp v30, v30, v30 row_ror:4 row_mask:0xf bank_mask:0xf bound_ctrl:1
	v_max_u32_dpp v32, v32, v32 row_ror:4 row_mask:0xf bank_mask:0xf bound_ctrl:1
	v_max_u32_dpp v31, v31, v31 row_ror:8 row_mask:0xf bank_mask:0xf bound_ctrl:1
	v_max_u32_dpp v33, v33, v33 row_ror:4 row_mask:0xf bank_mask:0xf bound_ctrl:1
	v_max_u32_dpp v30, v30, v30 row_ror:8 row_mask:0xf bank_mask:0xf bound_ctrl:1
	v_max_u32_dpp v32, v32, v32 row_ror:8 row_mask:0xf bank_mask:0xf bound_ctrl:1
	v_cmp_eq_u32_e64 s[0:1], v8, v31
	v_max_u32_dpp v33, v33, v33 row_ror:8 row_mask:0xf bank_mask:0xf bound_ctrl:1
	v_cmp_eq_u32_e32 vcc, v9, v30
	v_cndmask_b32_e64 v8, v8, v13, s[0:1]
	v_cndmask_b32_e64 v13, v13, v23, s[0:1]
	v_cndmask_b32_e64 v23, v23, v12, s[0:1]
	v_cndmask_b32_e64 v12, v12, 0, s[0:1]
	v_cmp_eq_u32_e64 s[0:1], v14, v32
	v_cndmask_b32_e32 v9, v9, v11, vcc
	v_cndmask_b32_e32 v11, v11, v22, vcc
	v_cndmask_b32_e32 v22, v22, v10, vcc
	v_cndmask_b32_e64 v10, v10, 0, vcc
	s_lshl_b64 vcc, s[78:79], s40
	v_cndmask_b32_e64 v14, v14, v24, s[0:1]
	v_cndmask_b32_e64 v24, v24, v25, s[0:1]
	v_cndmask_b32_e64 v25, v25, v15, s[0:1]
	v_cndmask_b32_e64 v15, v15, 0, s[0:1]
	v_cmp_eq_u32_e64 s[0:1], v26, v33
	s_add_i32 s40, s40, 1
	v_cndmask_b32_e32 v7, v7, v30, vcc
	v_cndmask_b32_e32 v6, v6, v31, vcc
	v_cndmask_b32_e32 v5, v5, v32, vcc
	v_cndmask_b32_e64 v26, v26, v28, s[0:1]
	v_cndmask_b32_e64 v28, v28, v29, s[0:1]
	v_cndmask_b32_e64 v29, v29, v27, s[0:1]
	v_cndmask_b32_e64 v27, v27, 0, s[0:1]
	s_cmp_lg_u32 s40, 8
	v_cndmask_b32_e32 v4, v4, v33, vcc
	s_cbranch_scc1 .LBB0_1375
	v_max_u32_dpp v31, v8, v8 row_ror:1 row_mask:0xf bank_mask:0xf bound_ctrl:1
	v_max_u32_dpp v30, v9, v9 row_ror:1 row_mask:0xf bank_mask:0xf bound_ctrl:1
	v_max_u32_dpp v32, v14, v14 row_ror:1 row_mask:0xf bank_mask:0xf bound_ctrl:1
	v_max_u32_dpp v31, v31, v31 row_ror:2 row_mask:0xf bank_mask:0xf bound_ctrl:1
	v_max_u32_dpp v33, v26, v26 row_ror:1 row_mask:0xf bank_mask:0xf bound_ctrl:1
	v_max_u32_dpp v30, v30, v30 row_ror:2 row_mask:0xf bank_mask:0xf bound_ctrl:1
	v_max_u32_dpp v32, v32, v32 row_ror:2 row_mask:0xf bank_mask:0xf bound_ctrl:1
	v_max_u32_dpp v31, v31, v31 row_ror:4 row_mask:0xf bank_mask:0xf bound_ctrl:1
	v_max_u32_dpp v33, v33, v33 row_ror:2 row_mask:0xf bank_mask:0xf bound_ctrl:1
	v_max_u32_dpp v30, v30, v30 row_ror:4 row_mask:0xf bank_mask:0xf bound_ctrl:1
	v_max_u32_dpp v32, v32, v32 row_ror:4 row_mask:0xf bank_mask:0xf bound_ctrl:1
	v_max_u32_dpp v31, v31, v31 row_ror:8 row_mask:0xf bank_mask:0xf bound_ctrl:1
	v_max_u32_dpp v33, v33, v33 row_ror:4 row_mask:0xf bank_mask:0xf bound_ctrl:1
	v_max_u32_dpp v30, v30, v30 row_ror:8 row_mask:0xf bank_mask:0xf bound_ctrl:1
	v_max_u32_dpp v32, v32, v32 row_ror:8 row_mask:0xf bank_mask:0xf bound_ctrl:1
	v_cmp_eq_u32_e64 s[0:1], v8, v31
	v_max_u32_dpp v33, v33, v33 row_ror:8 row_mask:0xf bank_mask:0xf bound_ctrl:1
	v_cmp_eq_u32_e32 vcc, v9, v30
	v_cndmask_b32_e64 v8, v8, v13, s[0:1]
	v_cndmask_b32_e64 v13, v13, v23, s[0:1]
	v_cndmask_b32_e64 v23, v23, v12, s[0:1]
	v_cndmask_b32_e64 v12, v12, 0, s[0:1]
	v_cmp_eq_u32_e64 s[0:1], v14, v32
	v_cndmask_b32_e32 v9, v9, v11, vcc
	v_cndmask_b32_e32 v11, v11, v22, vcc
	v_cndmask_b32_e32 v22, v22, v10, vcc
	v_cndmask_b32_e64 v10, v10, 0, vcc
	s_lshl_b64 vcc, s[78:79], s40
	v_cndmask_b32_e64 v14, v14, v24, s[0:1]
	v_cndmask_b32_e64 v24, v24, v25, s[0:1]
	v_cndmask_b32_e64 v25, v25, v15, s[0:1]
	v_cndmask_b32_e64 v15, v15, 0, s[0:1]
	v_cmp_eq_u32_e64 s[0:1], v26, v33
	s_add_i32 s40, s40, 1
	v_cndmask_b32_e32 v7, v7, v30, vcc
	v_cndmask_b32_e32 v6, v6, v31, vcc
	v_cndmask_b32_e32 v5, v5, v32, vcc
	v_cndmask_b32_e64 v26, v26, v28, s[0:1]
	v_cndmask_b32_e64 v28, v28, v29, s[0:1]
	v_cndmask_b32_e64 v29, v29, v27, s[0:1]
	v_cndmask_b32_e64 v27, v27, 0, s[0:1]
	v_cndmask_b32_e32 v4, v4, v33, vcc
	v_max_u32_dpp v31, v8, v8 row_ror:1 row_mask:0xf bank_mask:0xf bound_ctrl:1
	v_max_u32_dpp v30, v9, v9 row_ror:1 row_mask:0xf bank_mask:0xf bound_ctrl:1
	v_max_u32_dpp v32, v14, v14 row_ror:1 row_mask:0xf bank_mask:0xf bound_ctrl:1
	v_max_u32_dpp v31, v31, v31 row_ror:2 row_mask:0xf bank_mask:0xf bound_ctrl:1
	v_max_u32_dpp v33, v26, v26 row_ror:1 row_mask:0xf bank_mask:0xf bound_ctrl:1
	v_max_u32_dpp v30, v30, v30 row_ror:2 row_mask:0xf bank_mask:0xf bound_ctrl:1
	v_max_u32_dpp v32, v32, v32 row_ror:2 row_mask:0xf bank_mask:0xf bound_ctrl:1
	v_max_u32_dpp v31, v31, v31 row_ror:4 row_mask:0xf bank_mask:0xf bound_ctrl:1
	v_max_u32_dpp v33, v33, v33 row_ror:2 row_mask:0xf bank_mask:0xf bound_ctrl:1
	v_max_u32_dpp v30, v30, v30 row_ror:4 row_mask:0xf bank_mask:0xf bound_ctrl:1
	v_max_u32_dpp v32, v32, v32 row_ror:4 row_mask:0xf bank_mask:0xf bound_ctrl:1
	v_max_u32_dpp v31, v31, v31 row_ror:8 row_mask:0xf bank_mask:0xf bound_ctrl:1
	v_max_u32_dpp v33, v33, v33 row_ror:4 row_mask:0xf bank_mask:0xf bound_ctrl:1
	v_max_u32_dpp v30, v30, v30 row_ror:8 row_mask:0xf bank_mask:0xf bound_ctrl:1
	v_max_u32_dpp v32, v32, v32 row_ror:8 row_mask:0xf bank_mask:0xf bound_ctrl:1
	v_cmp_eq_u32_e64 s[0:1], v8, v31
	v_max_u32_dpp v33, v33, v33 row_ror:8 row_mask:0xf bank_mask:0xf bound_ctrl:1
	v_cmp_eq_u32_e32 vcc, v9, v30
	v_cndmask_b32_e64 v8, v8, v13, s[0:1]
	v_cndmask_b32_e64 v13, v13, v23, s[0:1]
	v_cndmask_b32_e64 v23, v23, v12, s[0:1]
	v_cndmask_b32_e64 v12, v12, 0, s[0:1]
	v_cmp_eq_u32_e64 s[0:1], v14, v32
	v_cndmask_b32_e32 v9, v9, v11, vcc
	v_cndmask_b32_e32 v11, v11, v22, vcc
	v_cndmask_b32_e32 v22, v22, v10, vcc
	v_cndmask_b32_e64 v10, v10, 0, vcc
	s_lshl_b64 vcc, s[78:79], s40
	v_cndmask_b32_e64 v14, v14, v24, s[0:1]
	v_cndmask_b32_e64 v24, v24, v25, s[0:1]
	v_cndmask_b32_e64 v25, v25, v15, s[0:1]
	v_cndmask_b32_e64 v15, v15, 0, s[0:1]
	v_cmp_eq_u32_e64 s[0:1], v26, v33
	s_add_i32 s40, s40, 1
	v_cndmask_b32_e32 v7, v7, v30, vcc
	v_cndmask_b32_e32 v6, v6, v31, vcc
	v_cndmask_b32_e32 v5, v5, v32, vcc
	v_cndmask_b32_e64 v26, v26, v28, s[0:1]
	v_cndmask_b32_e64 v28, v28, v29, s[0:1]
	v_cndmask_b32_e64 v29, v29, v27, s[0:1]
	v_cndmask_b32_e64 v27, v27, 0, s[0:1]
	v_cndmask_b32_e32 v4, v4, v33, vcc
	v_max_u32_dpp v31, v8, v8 row_ror:1 row_mask:0xf bank_mask:0xf bound_ctrl:1
	v_max_u32_dpp v30, v9, v9 row_ror:1 row_mask:0xf bank_mask:0xf bound_ctrl:1
	v_max_u32_dpp v32, v14, v14 row_ror:1 row_mask:0xf bank_mask:0xf bound_ctrl:1
	v_max_u32_dpp v31, v31, v31 row_ror:2 row_mask:0xf bank_mask:0xf bound_ctrl:1
	v_max_u32_dpp v33, v26, v26 row_ror:1 row_mask:0xf bank_mask:0xf bound_ctrl:1
	v_max_u32_dpp v30, v30, v30 row_ror:2 row_mask:0xf bank_mask:0xf bound_ctrl:1
	v_max_u32_dpp v32, v32, v32 row_ror:2 row_mask:0xf bank_mask:0xf bound_ctrl:1
	v_max_u32_dpp v31, v31, v31 row_ror:4 row_mask:0xf bank_mask:0xf bound_ctrl:1
	v_max_u32_dpp v33, v33, v33 row_ror:2 row_mask:0xf bank_mask:0xf bound_ctrl:1
	v_max_u32_dpp v30, v30, v30 row_ror:4 row_mask:0xf bank_mask:0xf bound_ctrl:1
	v_max_u32_dpp v32, v32, v32 row_ror:4 row_mask:0xf bank_mask:0xf bound_ctrl:1
	v_max_u32_dpp v31, v31, v31 row_ror:8 row_mask:0xf bank_mask:0xf bound_ctrl:1
	v_max_u32_dpp v33, v33, v33 row_ror:4 row_mask:0xf bank_mask:0xf bound_ctrl:1
	v_max_u32_dpp v30, v30, v30 row_ror:8 row_mask:0xf bank_mask:0xf bound_ctrl:1
	v_max_u32_dpp v32, v32, v32 row_ror:8 row_mask:0xf bank_mask:0xf bound_ctrl:1
	v_cmp_eq_u32_e64 s[0:1], v8, v31
	v_max_u32_dpp v33, v33, v33 row_ror:8 row_mask:0xf bank_mask:0xf bound_ctrl:1
	v_cmp_eq_u32_e32 vcc, v9, v30
	v_cndmask_b32_e64 v8, v8, v13, s[0:1]
	v_cndmask_b32_e64 v13, v13, v23, s[0:1]
	v_cndmask_b32_e64 v23, v23, v12, s[0:1]
	v_cndmask_b32_e64 v12, v12, 0, s[0:1]
	v_cmp_eq_u32_e64 s[0:1], v14, v32
	v_cndmask_b32_e32 v9, v9, v11, vcc
	v_cndmask_b32_e32 v11, v11, v22, vcc
	v_cndmask_b32_e32 v22, v22, v10, vcc
	v_cndmask_b32_e64 v10, v10, 0, vcc
	s_lshl_b64 vcc, s[78:79], s40
	v_cndmask_b32_e64 v14, v14, v24, s[0:1]
	v_cndmask_b32_e64 v24, v24, v25, s[0:1]
	v_cndmask_b32_e64 v25, v25, v15, s[0:1]
	v_cndmask_b32_e64 v15, v15, 0, s[0:1]
	v_cmp_eq_u32_e64 s[0:1], v26, v33
	s_add_i32 s40, s40, 1
	v_cndmask_b32_e32 v7, v7, v30, vcc
	v_cndmask_b32_e32 v6, v6, v31, vcc
	v_cndmask_b32_e32 v5, v5, v32, vcc
	v_cndmask_b32_e64 v26, v26, v28, s[0:1]
	v_cndmask_b32_e64 v28, v28, v29, s[0:1]
	v_cndmask_b32_e64 v29, v29, v27, s[0:1]
	v_cndmask_b32_e64 v27, v27, 0, s[0:1]
	v_cndmask_b32_e32 v4, v4, v33, vcc
	v_max_u32_dpp v31, v8, v8 row_ror:1 row_mask:0xf bank_mask:0xf bound_ctrl:1
	v_max_u32_dpp v30, v9, v9 row_ror:1 row_mask:0xf bank_mask:0xf bound_ctrl:1
	v_max_u32_dpp v32, v14, v14 row_ror:1 row_mask:0xf bank_mask:0xf bound_ctrl:1
	v_max_u32_dpp v31, v31, v31 row_ror:2 row_mask:0xf bank_mask:0xf bound_ctrl:1
	v_max_u32_dpp v33, v26, v26 row_ror:1 row_mask:0xf bank_mask:0xf bound_ctrl:1
	v_max_u32_dpp v30, v30, v30 row_ror:2 row_mask:0xf bank_mask:0xf bound_ctrl:1
	v_max_u32_dpp v32, v32, v32 row_ror:2 row_mask:0xf bank_mask:0xf bound_ctrl:1
	v_max_u32_dpp v31, v31, v31 row_ror:4 row_mask:0xf bank_mask:0xf bound_ctrl:1
	v_max_u32_dpp v33, v33, v33 row_ror:2 row_mask:0xf bank_mask:0xf bound_ctrl:1
	v_max_u32_dpp v30, v30, v30 row_ror:4 row_mask:0xf bank_mask:0xf bound_ctrl:1
	v_max_u32_dpp v32, v32, v32 row_ror:4 row_mask:0xf bank_mask:0xf bound_ctrl:1
	v_max_u32_dpp v31, v31, v31 row_ror:8 row_mask:0xf bank_mask:0xf bound_ctrl:1
	v_max_u32_dpp v33, v33, v33 row_ror:4 row_mask:0xf bank_mask:0xf bound_ctrl:1
	v_max_u32_dpp v30, v30, v30 row_ror:8 row_mask:0xf bank_mask:0xf bound_ctrl:1
	v_max_u32_dpp v32, v32, v32 row_ror:8 row_mask:0xf bank_mask:0xf bound_ctrl:1
	v_cmp_eq_u32_e64 s[0:1], v8, v31
	v_max_u32_dpp v33, v33, v33 row_ror:8 row_mask:0xf bank_mask:0xf bound_ctrl:1
	v_cmp_eq_u32_e32 vcc, v9, v30
	v_cndmask_b32_e64 v8, v8, v13, s[0:1]
	v_cndmask_b32_e64 v13, v13, v23, s[0:1]
	v_cndmask_b32_e64 v23, v23, v12, s[0:1]
	v_cndmask_b32_e64 v12, v12, 0, s[0:1]
	v_cmp_eq_u32_e64 s[0:1], v14, v32
	v_cndmask_b32_e32 v9, v9, v11, vcc
	v_cndmask_b32_e32 v11, v11, v22, vcc
	v_cndmask_b32_e32 v22, v22, v10, vcc
	v_cndmask_b32_e64 v10, v10, 0, vcc
	s_lshl_b64 vcc, s[78:79], s40
	v_cndmask_b32_e64 v14, v14, v24, s[0:1]
	v_cndmask_b32_e64 v24, v24, v25, s[0:1]
	v_cndmask_b32_e64 v25, v25, v15, s[0:1]
	v_cndmask_b32_e64 v15, v15, 0, s[0:1]
	v_cmp_eq_u32_e64 s[0:1], v26, v33
	s_add_i32 s40, s40, 1
	v_cndmask_b32_e32 v7, v7, v30, vcc
	v_cndmask_b32_e32 v6, v6, v31, vcc
	v_cndmask_b32_e32 v5, v5, v32, vcc
	v_cndmask_b32_e64 v26, v26, v28, s[0:1]
	v_cndmask_b32_e64 v28, v28, v29, s[0:1]
	v_cndmask_b32_e64 v29, v29, v27, s[0:1]
	v_cndmask_b32_e64 v27, v27, 0, s[0:1]
	v_cndmask_b32_e32 v4, v4, v33, vcc
	v_max_u32_dpp v31, v8, v8 row_ror:1 row_mask:0xf bank_mask:0xf bound_ctrl:1
	v_max_u32_dpp v30, v9, v9 row_ror:1 row_mask:0xf bank_mask:0xf bound_ctrl:1
	v_max_u32_dpp v32, v14, v14 row_ror:1 row_mask:0xf bank_mask:0xf bound_ctrl:1
	v_max_u32_dpp v31, v31, v31 row_ror:2 row_mask:0xf bank_mask:0xf bound_ctrl:1
	v_max_u32_dpp v33, v26, v26 row_ror:1 row_mask:0xf bank_mask:0xf bound_ctrl:1
	v_max_u32_dpp v30, v30, v30 row_ror:2 row_mask:0xf bank_mask:0xf bound_ctrl:1
	v_max_u32_dpp v32, v32, v32 row_ror:2 row_mask:0xf bank_mask:0xf bound_ctrl:1
	v_max_u32_dpp v31, v31, v31 row_ror:4 row_mask:0xf bank_mask:0xf bound_ctrl:1
	v_max_u32_dpp v33, v33, v33 row_ror:2 row_mask:0xf bank_mask:0xf bound_ctrl:1
	v_max_u32_dpp v30, v30, v30 row_ror:4 row_mask:0xf bank_mask:0xf bound_ctrl:1
	v_max_u32_dpp v32, v32, v32 row_ror:4 row_mask:0xf bank_mask:0xf bound_ctrl:1
	v_max_u32_dpp v31, v31, v31 row_ror:8 row_mask:0xf bank_mask:0xf bound_ctrl:1
	v_max_u32_dpp v33, v33, v33 row_ror:4 row_mask:0xf bank_mask:0xf bound_ctrl:1
	v_max_u32_dpp v30, v30, v30 row_ror:8 row_mask:0xf bank_mask:0xf bound_ctrl:1
	v_max_u32_dpp v32, v32, v32 row_ror:8 row_mask:0xf bank_mask:0xf bound_ctrl:1
	v_cmp_eq_u32_e64 s[0:1], v8, v31
	v_max_u32_dpp v33, v33, v33 row_ror:8 row_mask:0xf bank_mask:0xf bound_ctrl:1
	v_cmp_eq_u32_e32 vcc, v9, v30
	v_cndmask_b32_e64 v8, v8, v13, s[0:1]
	v_cndmask_b32_e64 v13, v13, v23, s[0:1]
	v_cndmask_b32_e64 v23, v23, v12, s[0:1]
	v_cmp_eq_u32_e64 s[0:1], v14, v32
	v_cndmask_b32_e32 v9, v9, v11, vcc
	v_cndmask_b32_e32 v11, v11, v22, vcc
	v_cndmask_b32_e32 v22, v22, v10, vcc
	s_lshl_b64 vcc, s[78:79], s40
	v_cndmask_b32_e64 v14, v14, v24, s[0:1]
	v_cndmask_b32_e64 v24, v24, v25, s[0:1]
	v_cndmask_b32_e64 v25, v25, v15, s[0:1]
	v_cmp_eq_u32_e64 s[0:1], v26, v33
	s_add_i32 s40, s40, 1
	v_cndmask_b32_e32 v7, v7, v30, vcc
	v_cndmask_b32_e32 v6, v6, v31, vcc
	v_cndmask_b32_e32 v5, v5, v32, vcc
	v_cndmask_b32_e64 v26, v26, v28, s[0:1]
	v_cndmask_b32_e64 v28, v28, v29, s[0:1]
	v_cndmask_b32_e64 v29, v29, v27, s[0:1]
	v_cndmask_b32_e32 v4, v4, v33, vcc
	v_max_u32_dpp v31, v8, v8 row_ror:1 row_mask:0xf bank_mask:0xf bound_ctrl:1
	v_max_u32_dpp v30, v9, v9 row_ror:1 row_mask:0xf bank_mask:0xf bound_ctrl:1
	v_max_u32_dpp v32, v14, v14 row_ror:1 row_mask:0xf bank_mask:0xf bound_ctrl:1
	v_max_u32_dpp v31, v31, v31 row_ror:2 row_mask:0xf bank_mask:0xf bound_ctrl:1
	v_max_u32_dpp v33, v26, v26 row_ror:1 row_mask:0xf bank_mask:0xf bound_ctrl:1
	v_max_u32_dpp v30, v30, v30 row_ror:2 row_mask:0xf bank_mask:0xf bound_ctrl:1
	v_max_u32_dpp v32, v32, v32 row_ror:2 row_mask:0xf bank_mask:0xf bound_ctrl:1
	v_max_u32_dpp v31, v31, v31 row_ror:4 row_mask:0xf bank_mask:0xf bound_ctrl:1
	v_max_u32_dpp v33, v33, v33 row_ror:2 row_mask:0xf bank_mask:0xf bound_ctrl:1
	v_max_u32_dpp v30, v30, v30 row_ror:4 row_mask:0xf bank_mask:0xf bound_ctrl:1
	v_max_u32_dpp v32, v32, v32 row_ror:4 row_mask:0xf bank_mask:0xf bound_ctrl:1
	v_max_u32_dpp v31, v31, v31 row_ror:8 row_mask:0xf bank_mask:0xf bound_ctrl:1
	v_max_u32_dpp v33, v33, v33 row_ror:4 row_mask:0xf bank_mask:0xf bound_ctrl:1
	v_max_u32_dpp v30, v30, v30 row_ror:8 row_mask:0xf bank_mask:0xf bound_ctrl:1
	v_max_u32_dpp v32, v32, v32 row_ror:8 row_mask:0xf bank_mask:0xf bound_ctrl:1
	v_cmp_eq_u32_e64 s[0:1], v8, v31
	v_max_u32_dpp v33, v33, v33 row_ror:8 row_mask:0xf bank_mask:0xf bound_ctrl:1
	v_cmp_eq_u32_e32 vcc, v9, v30
	v_cndmask_b32_e64 v8, v8, v13, s[0:1]
	v_cndmask_b32_e64 v13, v13, v23, s[0:1]
	v_cmp_eq_u32_e64 s[0:1], v14, v32
	v_cndmask_b32_e32 v9, v9, v11, vcc
	v_cndmask_b32_e32 v11, v11, v22, vcc
	s_lshl_b64 vcc, s[78:79], s40
	v_cndmask_b32_e64 v14, v14, v24, s[0:1]
	v_cndmask_b32_e64 v24, v24, v25, s[0:1]
	v_cmp_eq_u32_e64 s[0:1], v26, v33
	s_add_i32 s40, s40, 1
	v_cndmask_b32_e32 v7, v7, v30, vcc
	v_cndmask_b32_e32 v6, v6, v31, vcc
	v_cndmask_b32_e32 v5, v5, v32, vcc
	v_cndmask_b32_e64 v26, v26, v28, s[0:1]
	v_cndmask_b32_e64 v28, v28, v29, s[0:1]
	v_cndmask_b32_e32 v4, v4, v33, vcc
	v_max_u32_dpp v31, v8, v8 row_ror:1 row_mask:0xf bank_mask:0xf bound_ctrl:1
	v_max_u32_dpp v30, v9, v9 row_ror:1 row_mask:0xf bank_mask:0xf bound_ctrl:1
	v_max_u32_dpp v32, v14, v14 row_ror:1 row_mask:0xf bank_mask:0xf bound_ctrl:1
	v_max_u32_dpp v31, v31, v31 row_ror:2 row_mask:0xf bank_mask:0xf bound_ctrl:1
	v_max_u32_dpp v33, v26, v26 row_ror:1 row_mask:0xf bank_mask:0xf bound_ctrl:1
	v_max_u32_dpp v30, v30, v30 row_ror:2 row_mask:0xf bank_mask:0xf bound_ctrl:1
	v_max_u32_dpp v32, v32, v32 row_ror:2 row_mask:0xf bank_mask:0xf bound_ctrl:1
	v_max_u32_dpp v31, v31, v31 row_ror:4 row_mask:0xf bank_mask:0xf bound_ctrl:1
	v_max_u32_dpp v33, v33, v33 row_ror:2 row_mask:0xf bank_mask:0xf bound_ctrl:1
	v_max_u32_dpp v30, v30, v30 row_ror:4 row_mask:0xf bank_mask:0xf bound_ctrl:1
	v_max_u32_dpp v32, v32, v32 row_ror:4 row_mask:0xf bank_mask:0xf bound_ctrl:1
	v_max_u32_dpp v31, v31, v31 row_ror:8 row_mask:0xf bank_mask:0xf bound_ctrl:1
	v_max_u32_dpp v33, v33, v33 row_ror:4 row_mask:0xf bank_mask:0xf bound_ctrl:1
	v_max_u32_dpp v30, v30, v30 row_ror:8 row_mask:0xf bank_mask:0xf bound_ctrl:1
	v_max_u32_dpp v32, v32, v32 row_ror:8 row_mask:0xf bank_mask:0xf bound_ctrl:1
	v_cmp_eq_u32_e64 s[0:1], v8, v31
	v_max_u32_dpp v33, v33, v33 row_ror:8 row_mask:0xf bank_mask:0xf bound_ctrl:1
	v_cmp_eq_u32_e32 vcc, v9, v30
	v_cndmask_b32_e64 v8, v8, v13, s[0:1]
	v_cmp_eq_u32_e64 s[0:1], v14, v32
	v_cndmask_b32_e32 v9, v9, v11, vcc
	s_lshl_b64 vcc, s[78:79], s40
	v_cndmask_b32_e64 v14, v14, v24, s[0:1]
	v_cmp_eq_u32_e64 s[0:1], v26, v33
	s_add_i32 s40, s40, 1
	v_cndmask_b32_e32 v7, v7, v30, vcc
	v_cndmask_b32_e32 v6, v6, v31, vcc
	v_cndmask_b32_e32 v5, v5, v32, vcc
	v_cndmask_b32_e64 v26, v26, v28, s[0:1]
	v_cndmask_b32_e32 v4, v4, v33, vcc
	v_max_u32_dpp v31, v8, v8 row_ror:1 row_mask:0xf bank_mask:0xf bound_ctrl:1
	v_max_u32_dpp v30, v9, v9 row_ror:1 row_mask:0xf bank_mask:0xf bound_ctrl:1
	v_max_u32_dpp v32, v14, v14 row_ror:1 row_mask:0xf bank_mask:0xf bound_ctrl:1
	v_max_u32_dpp v31, v31, v31 row_ror:2 row_mask:0xf bank_mask:0xf bound_ctrl:1
	v_max_u32_dpp v33, v26, v26 row_ror:1 row_mask:0xf bank_mask:0xf bound_ctrl:1
	v_max_u32_dpp v30, v30, v30 row_ror:2 row_mask:0xf bank_mask:0xf bound_ctrl:1
	v_max_u32_dpp v32, v32, v32 row_ror:2 row_mask:0xf bank_mask:0xf bound_ctrl:1
	v_max_u32_dpp v31, v31, v31 row_ror:4 row_mask:0xf bank_mask:0xf bound_ctrl:1
	v_max_u32_dpp v33, v33, v33 row_ror:2 row_mask:0xf bank_mask:0xf bound_ctrl:1
	v_max_u32_dpp v30, v30, v30 row_ror:4 row_mask:0xf bank_mask:0xf bound_ctrl:1
	v_max_u32_dpp v32, v32, v32 row_ror:4 row_mask:0xf bank_mask:0xf bound_ctrl:1
	v_max_u32_dpp v31, v31, v31 row_ror:8 row_mask:0xf bank_mask:0xf bound_ctrl:1
	v_max_u32_dpp v33, v33, v33 row_ror:4 row_mask:0xf bank_mask:0xf bound_ctrl:1
	v_max_u32_dpp v30, v30, v30 row_ror:8 row_mask:0xf bank_mask:0xf bound_ctrl:1
	v_max_u32_dpp v32, v32, v32 row_ror:8 row_mask:0xf bank_mask:0xf bound_ctrl:1
	v_max_u32_dpp v33, v33, v33 row_ror:8 row_mask:0xf bank_mask:0xf bound_ctrl:1
	s_lshl_b64 vcc, s[78:79], s40
	v_cndmask_b32_e32 v7, v7, v30, vcc
	v_cndmask_b32_e32 v6, v6, v31, vcc
	v_cndmask_b32_e32 v5, v5, v32, vcc
	v_cndmask_b32_e32 v4, v4, v33, vcc
	v_max_u32_dpp v15, v7, v7 row_ror:1 row_mask:0xf bank_mask:0xf bound_ctrl:1
	v_cmp_lt_i32_e32 vcc, -1, v7
	v_bitop3_b32 v11, v18, s60, v18 bitop3:0xc
	v_max_u32_dpp v15, v15, v15 row_ror:2 row_mask:0xf bank_mask:0xf bound_ctrl:1
	v_cndmask_b32_e64 v14, v217, -1, vcc
	v_bitop3_b32 v14, v14, v7, s59 bitop3:0x78
	v_max_u32_dpp v15, v15, v15 row_ror:4 row_mask:0xf bank_mask:0xf bound_ctrl:1
	v_not_b32_e32 v13, v7
	v_lshrrev_b32_e32 v13, 4, v13
	v_max_u32_dpp v15, v15, v15 row_ror:8 row_mask:0xf bank_mask:0xf bound_ctrl:1
	v_cmp_lt_i32_e32 vcc, -1, v15
	v_and_or_b32 v13, v13, 15, v195
	v_lshlrev_b32_e32 v13, 2, v13
	v_cndmask_b32_e64 v18, v217, -1, vcc
	v_bitop3_b32 v15, v18, v15, s59 bitop3:0x78
	v_sub_f32_e32 v14, v14, v15
	v_mul_f32_e32 v14, 0x3fb8aa3b, v14
	v_exp_f32_e32 v14, v14
	ds_bpermute_b32 v11, v13, v11
	v_bitop3_b32 v7, v7, v195, 15 bitop3:0xce
	v_bitop3_b32 v0, v0, s60, v0 bitop3:0xc
	v_add_f32_dpp v13, v14, v14 row_ror:1 row_mask:0xf bank_mask:0xf bound_ctrl:1
	v_lshlrev_b32_e32 v7, 2, v7
	ds_bpermute_b32 v0, v7, v0
	v_add_f32_dpp v13, v13, v13 row_ror:2 row_mask:0xf bank_mask:0xf bound_ctrl:1
	v_bitop3_b32 v10, v19, s60, v19 bitop3:0xc
	v_bitop3_b32 v9, v20, s60, v20 bitop3:0xc
	v_add_f32_dpp v13, v13, v13 row_ror:4 row_mask:0xf bank_mask:0xf bound_ctrl:1
	v_lshl_or_b32 v12, s33, 4, v171
	s_waitcnt lgkmcnt(0)
	v_lshl_add_u32 v0, v11, 7, v0
	v_add_f32_dpp v13, v13, v13 row_ror:8 row_mask:0xf bank_mask:0xf bound_ctrl:1
	v_div_scale_f32 v15, s[0:1], v13, v13, v14
	v_rcp_f32_e32 v18, v15
	v_bitop3_b32 v1, v1, s60, v1 bitop3:0xc
	v_bitop3_b32 v2, v2, s60, v2 bitop3:0xc
	v_bitop3_b32 v3, v3, s60, v3 bitop3:0xc
	v_fma_f32 v7, -v15, v18, 1.0
	v_fmac_f32_e32 v18, v7, v18
	v_div_scale_f32 v7, vcc, v14, v13, v14
	v_mul_f32_e32 v19, v7, v18
	v_fma_f32 v20, -v15, v19, v7
	v_fmac_f32_e32 v19, v20, v18
	v_fma_f32 v7, -v15, v19, v7
	v_div_fmas_f32 v7, v7, v18, v19
	v_div_fixup_f32 v7, v7, v13, v14
	v_or_b32_e32 v13, v12, v183
	v_lshl_add_u32 v11, v13, 1, s63
	v_cvt_f16_f32_e32 v7, v7
	v_max_u32_dpp v13, v6, v6 row_ror:1 row_mask:0xf bank_mask:0xf bound_ctrl:1
	v_cmp_lt_i32_e32 vcc, -1, v6
	ds_write_b16 v11, v0
	ds_write_b16 v11, v7 offset:32768
	v_max_u32_dpp v13, v13, v13 row_ror:2 row_mask:0xf bank_mask:0xf bound_ctrl:1
	v_cndmask_b32_e64 v7, v217, -1, vcc
	v_bitop3_b32 v7, v7, v6, s59 bitop3:0x78
	v_max_u32_dpp v13, v13, v13 row_ror:4 row_mask:0xf bank_mask:0xf bound_ctrl:1
	v_not_b32_e32 v0, v6
	v_lshrrev_b32_e32 v0, 4, v0
	v_max_u32_dpp v13, v13, v13 row_ror:8 row_mask:0xf bank_mask:0xf bound_ctrl:1
	v_cmp_lt_i32_e32 vcc, -1, v13
	v_and_or_b32 v0, v0, 15, v195
	v_lshlrev_b32_e32 v0, 2, v0
	v_cndmask_b32_e64 v14, v217, -1, vcc
	v_bitop3_b32 v13, v14, v13, s59 bitop3:0x78
	v_sub_f32_e32 v7, v7, v13
	v_mul_f32_e32 v7, 0x3fb8aa3b, v7
	v_exp_f32_e32 v7, v7
	ds_bpermute_b32 v0, v0, v10
	v_bitop3_b32 v6, v6, v195, 15 bitop3:0xce
	v_lshlrev_b32_e32 v6, 2, v6
	v_add_f32_dpp v10, v7, v7 row_ror:1 row_mask:0xf bank_mask:0xf bound_ctrl:1
	ds_bpermute_b32 v1, v6, v1
	v_bitop3_b32 v8, v21, s60, v21 bitop3:0xc
	v_add_f32_dpp v10, v10, v10 row_ror:2 row_mask:0xf bank_mask:0xf bound_ctrl:1
	s_waitcnt lgkmcnt(0)
	v_lshl_add_u32 v0, v0, 7, v1
	v_add_f32_dpp v10, v10, v10 row_ror:4 row_mask:0xf bank_mask:0xf bound_ctrl:1
	ds_write_b16 v11, v0 offset:256
	v_not_b32_e32 v1, v5
	v_add_f32_dpp v10, v10, v10 row_ror:8 row_mask:0xf bank_mask:0xf bound_ctrl:1
	v_div_scale_f32 v13, s[0:1], v10, v10, v7
	v_rcp_f32_e32 v14, v13
	v_lshrrev_b32_e32 v1, 4, v1
	v_and_or_b32 v1, v1, 15, v195
	v_lshlrev_b32_e32 v1, 2, v1
	v_fma_f32 v6, -v13, v14, 1.0
	v_fmac_f32_e32 v14, v6, v14
	v_div_scale_f32 v6, vcc, v7, v10, v7
	v_mul_f32_e32 v15, v6, v14
	v_fma_f32 v18, -v13, v15, v6
	v_fmac_f32_e32 v15, v18, v14
	v_fma_f32 v6, -v13, v15, v6
	v_div_fmas_f32 v6, v6, v14, v15
	v_div_fixup_f32 v6, v6, v10, v7
	v_max_u32_dpp v7, v5, v5 row_ror:1 row_mask:0xf bank_mask:0xf bound_ctrl:1
	v_cmp_lt_i32_e32 vcc, -1, v5
	v_cvt_f16_f32_e32 v0, v6
	v_max_u32_dpp v7, v7, v7 row_ror:2 row_mask:0xf bank_mask:0xf bound_ctrl:1
	v_cndmask_b32_e64 v6, v217, -1, vcc
	v_bitop3_b32 v6, v6, v5, s59 bitop3:0x78
	v_max_u32_dpp v7, v7, v7 row_ror:4 row_mask:0xf bank_mask:0xf bound_ctrl:1
	ds_bpermute_b32 v1, v1, v9
	v_bitop3_b32 v5, v5, v195, 15 bitop3:0xce
	v_max_u32_dpp v7, v7, v7 row_ror:8 row_mask:0xf bank_mask:0xf bound_ctrl:1
	v_cmp_lt_i32_e32 vcc, -1, v7
	v_lshlrev_b32_e32 v5, 2, v5
	ds_bpermute_b32 v2, v5, v2
	v_cndmask_b32_e64 v10, v217, -1, vcc
	v_bitop3_b32 v7, v10, v7, s59 bitop3:0x78
	v_sub_f32_e32 v6, v6, v7
	v_mul_f32_e32 v6, 0x3fb8aa3b, v6
	v_exp_f32_e32 v6, v6
	ds_write_b16 v11, v0 offset:33024
	s_waitcnt lgkmcnt(1)
	v_lshl_add_u32 v0, v1, 7, v2
	v_max_u32_dpp v2, v4, v4 row_ror:1 row_mask:0xf bank_mask:0xf bound_ctrl:1
	v_add_f32_dpp v7, v6, v6 row_ror:1 row_mask:0xf bank_mask:0xf bound_ctrl:1
	s_nop 0
	v_max_u32_dpp v2, v2, v2 row_ror:2 row_mask:0xf bank_mask:0xf bound_ctrl:1
	v_add_f32_dpp v7, v7, v7 row_ror:2 row_mask:0xf bank_mask:0xf bound_ctrl:1
	s_nop 0
	v_max_u32_dpp v2, v2, v2 row_ror:4 row_mask:0xf bank_mask:0xf bound_ctrl:1
	v_add_f32_dpp v7, v7, v7 row_ror:4 row_mask:0xf bank_mask:0xf bound_ctrl:1
	s_nop 0
	v_max_u32_dpp v2, v2, v2 row_ror:8 row_mask:0xf bank_mask:0xf bound_ctrl:1
	v_add_f32_dpp v7, v7, v7 row_ror:8 row_mask:0xf bank_mask:0xf bound_ctrl:1
	v_div_scale_f32 v9, s[0:1], v7, v7, v6
	v_rcp_f32_e32 v10, v9
	s_nop 0
	v_fma_f32 v5, -v9, v10, 1.0
	v_fmac_f32_e32 v10, v5, v10
	v_div_scale_f32 v5, vcc, v6, v7, v6
	v_mul_f32_e32 v13, v5, v10
	v_fma_f32 v14, -v9, v13, v5
	v_fmac_f32_e32 v13, v14, v10
	v_fma_f32 v5, -v9, v13, v5
	v_div_fmas_f32 v5, v5, v10, v13
	v_div_fixup_f32 v5, v5, v7, v6
	v_cvt_f16_f32_e32 v5, v5
	v_cmp_lt_i32_e32 vcc, -1, v4
	ds_write_b16 v11, v0 offset:512
	ds_write_b16 v11, v5 offset:33280
	v_cndmask_b32_e64 v1, v217, -1, vcc
	v_cmp_lt_i32_e32 vcc, -1, v2
	v_bitop3_b32 v1, v1, v4, s59 bitop3:0x78
	v_not_b32_e32 v0, v4
	v_cndmask_b32_e64 v5, v217, -1, vcc
	v_bitop3_b32 v2, v5, v2, s59 bitop3:0x78
	v_sub_f32_e32 v1, v1, v2
	v_mul_f32_e32 v1, 0x3fb8aa3b, v1
	v_exp_f32_e32 v1, v1
	v_bitop3_b32 v4, v4, v195, 15 bitop3:0xce
	v_lshlrev_b32_e32 v4, 2, v4
	v_lshrrev_b32_e32 v0, 4, v0
	v_add_f32_dpp v2, v1, v1 row_ror:1 row_mask:0xf bank_mask:0xf bound_ctrl:1
	ds_bpermute_b32 v3, v4, v3
	v_and_or_b32 v0, v0, 15, v195
	v_add_f32_dpp v2, v2, v2 row_ror:2 row_mask:0xf bank_mask:0xf bound_ctrl:1
	v_lshlrev_b32_e32 v0, 2, v0
	ds_bpermute_b32 v0, v0, v8
	v_add_f32_dpp v2, v2, v2 row_ror:4 row_mask:0xf bank_mask:0xf bound_ctrl:1
	s_waitcnt lgkmcnt(0)
	v_lshl_add_u32 v0, v0, 7, v3
	v_add_f32_dpp v2, v2, v2 row_ror:8 row_mask:0xf bank_mask:0xf bound_ctrl:1
	v_div_scale_f32 v5, s[0:1], v2, v2, v1
	v_rcp_f32_e32 v6, v5
	s_add_i32 s0, s33, 1
	s_cmp_lg_u32 s33, 7
	s_cselect_b32 s1, s0, 7
	v_fma_f32 v4, -v5, v6, 1.0
	v_fmac_f32_e32 v6, v4, v6
	v_div_scale_f32 v4, vcc, v1, v2, v1
	v_mul_f32_e32 v7, v4, v6
	v_fma_f32 v8, -v5, v7, v4
	v_fmac_f32_e32 v7, v8, v6
	v_fma_f32 v4, -v5, v7, v4
	v_div_fmas_f32 v4, v4, v6, v7
	v_div_fixup_f32 v1, v4, v2, v1
	v_add_u32_e32 v2, v12, v182
	v_cvt_f16_f32_e32 v1, v1
	v_lshl_or_b32 v2, v2, 1, v218
	s_lshl_b32 s40, s1, 16
	v_add_u32_e32 v2, s63, v2
	s_cmp_lt_u32 s1, 4
	ds_write_b16 v2, v0
	ds_write_b16 v2, v1 offset:32768
	v_lshl_add_u64 v[0:1], v[154:155], 0, s[40:41]
	s_cselect_b32 s33, s3, s56
	s_cselect_b32 s40, s2, s55
	v_mov_b32_e32 v2, s40
	v_mov_b32_e32 v3, s33
	s_lshl_b32 s1, s1, 9
	v_lshl_add_u64 v[2:3], v[16:17], 1, v[2:3]
	s_and_b32 s40, s1, 0x600
	v_lshl_add_u64 v[2:3], v[2:3], 0, s[40:41]
	v_lshl_add_u64 v[12:13], v[2:3], 0, v[148:149]
	s_cmp_eq_u32 s0, 8
	s_mov_b32 s33, s0
	s_cbranch_scc0 .LBB0_1346
	s_waitcnt lgkmcnt(0)
	s_barrier
	ds_read_b128 v[0:3], v185
	ds_read_b128 v[40:43], v185 offset:16
	s_ashr_i32 s49, s48, 31
	s_lshl_b64 s[0:1], s[48:49], 10
	v_lshl_add_u64 v[144:145], v[152:153], 0, s[0:1]
	s_waitcnt lgkmcnt(1)
	v_lshlrev_b32_e32 v4, 7, v0
	v_bfe_u32 v0, v0, 16, 16
	v_and_or_b32 v64, v4, s68, v150
	v_lshl_or_b32 v0, v0, 7, v150
	v_lshlrev_b32_e32 v4, 7, v1
	v_and_or_b32 v4, v4, s68, v150
	global_load_dwordx4 v[60:63], v0, s[26:27]
	global_load_dwordx4 v[56:59], v4, s[26:27]
	v_bfe_u32 v0, v1, 16, 16
	v_lshl_or_b32 v0, v0, 7, v150
	v_lshlrev_b32_e32 v1, 7, v2
	v_and_or_b32 v1, v1, s68, v150
	global_load_dwordx4 v[52:55], v0, s[26:27]
	global_load_dwordx4 v[48:51], v1, s[26:27]
	v_bfe_u32 v0, v2, 16, 16
	v_lshl_or_b32 v0, v0, 7, v150
	v_lshlrev_b32_e32 v1, 7, v3
	v_and_or_b32 v1, v1, s68, v150
	global_load_dwordx4 v[44:47], v0, s[26:27]
	global_load_dwordx4 v[36:39], v1, s[26:27]
	v_bfe_u32 v0, v3, 16, 16
	v_lshl_or_b32 v0, v0, 7, v150
	s_waitcnt lgkmcnt(0)
	v_lshlrev_b32_e32 v1, 7, v40
	v_and_or_b32 v1, v1, s68, v150
	global_load_dwordx4 v[32:35], v0, s[26:27]
	global_load_dwordx4 v[28:31], v1, s[26:27]
	v_bfe_u32 v0, v40, 16, 16
	v_lshl_or_b32 v0, v0, 7, v150
	v_lshlrev_b32_e32 v1, 7, v41
	v_and_or_b32 v1, v1, s68, v150
	global_load_dwordx4 v[24:27], v0, s[26:27]
	global_load_dwordx4 v[20:23], v1, s[26:27]
	v_bfe_u32 v0, v41, 16, 16
	v_lshl_or_b32 v0, v0, 7, v150
	v_lshlrev_b32_e32 v1, 7, v42
	v_and_or_b32 v1, v1, s68, v150
	global_load_dwordx4 v[16:19], v0, s[26:27]
	global_load_dwordx4 v[12:15], v1, s[26:27]
	v_bfe_u32 v0, v42, 16, 16
	v_lshl_or_b32 v0, v0, 7, v150
	v_lshlrev_b32_e32 v1, 7, v43
	v_and_or_b32 v1, v1, s68, v150
	global_load_dwordx4 v[8:11], v0, s[26:27]
	global_load_dwordx4 v[4:7], v1, s[26:27]
	v_bfe_u32 v0, v43, 16, 16
	v_lshl_or_b32 v0, v0, 7, v150
	global_load_dwordx4 v[0:3], v0, s[26:27]
	s_nop 0
	global_load_dwordx4 v[64:67], v64, s[26:27]
	s_nop 0
	global_load_dwordx4 v[40:43], v[144:145], off
	ds_read_b128 v[140:143], v185 offset:256
	ds_read_b128 v[136:139], v185 offset:272
	s_mov_b32 s76, 0
	s_branch .LBB0_1379
